# cross-lane reduction steps fused into v_add_f32_dpp (97 sites in P0/P4/P7), bitwise identical sums
# speedup vs baseline: 1.0813x; 1.0036x over previous
; __device__ __forceinline__ unsigned pk2(float lo, float hi) { const f32x2 v = {lo, hi}; const bf16x2_t b = __builtin_convertvector(v, bf16x2_t); return __builtin_bit_cast(unsigned, b); }
; __device__ __forceinline__ void phase0(const Ctx& C) {
;     ...
;     for (int row = gw; row < T_; row += 4 * NGW) {
;         f32x4 v[4][4];
; #pragma unroll
;         for (int r = 0; r < 4; ++r) { const int rw = (row + r * NGW < T_) ? row + r * NGW : row; const f32x4* xa = (const f32x4*)(x + (size_t)rw * D_) + lane;
; #pragma unroll
;             for (int j = 0; j < 4; ++j) v[r][j] = xa[64 * j]; }
; #pragma unroll
;         for (int r = 0; r < 4; ++r) {
;             const int rw = row + r * NGW; const bool has = rw < T_;
;             float s = 0.f; u32x2* oa = (u32x2*)(xb + (size_t)(has ? rw : row) * D_) + lane;
; #pragma unroll
;             for (int j = 0; j < 4; ++j) {
;                 s += (v[r][j][0] * v[r][j][0] + v[r][j][1] * v[r][j][1]) + (v[r][j][2] * v[r][j][2] + v[r][j][3] * v[r][j][3]);
;                 if (has) { u32x2 w; w.x = pk2(v[r][j][0], v[r][j][1]); w.y = pk2(v[r][j][2], v[r][j][3]); oa[64 * j] = w; }
;             }
;             s = wave_sum(s);
;             if (has && lane < 16) ssq[(size_t)rw * 16 + lane] = lane == 0 ? s : 0.f;
.LBB0_156:
	s_ashr_i32 s11, s10, 31
	s_lshl_b64 s[4:5], s[10:11], 12
	s_add_i32 s14, s10, s0
	s_cmpk_lt_i32 s14, 0x4000
	s_waitcnt lgkmcnt(0)
	s_cselect_b64 s[42:43], -1, 0
	v_lshl_add_u64 v[2:3], v[50:51], 0, s[4:5]
	s_and_b64 s[4:5], s[42:43], exec
	s_cselect_b32 s44, s14, s10
	global_load_dwordx4 v[56:59], v[2:3], off
	global_load_dwordx4 v[60:63], v[2:3], off offset:1024
	global_load_dwordx4 v[64:67], v[2:3], off offset:2048
	global_load_dwordx4 v[68:71], v[2:3], off offset:3072
	s_ashr_i32 s45, s44, 31
	s_add_i32 s18, s1, s10
	s_lshl_b64 s[4:5], s[44:45], 12
	s_cmpk_lt_i32 s18, 0x4000
	s_cselect_b64 s[36:37], -1, 0
	v_lshl_add_u64 v[2:3], v[50:51], 0, s[4:5]
	s_and_b64 s[4:5], s[36:37], exec
	s_cselect_b32 s40, s18, s10
	s_ashr_i32 s41, s40, 31
	s_add_i32 s16, s2, s10
	s_lshl_b64 s[4:5], s[40:41], 12
	s_cmpk_lt_i32 s16, 0x4000
	s_cselect_b64 s[20:21], -1, 0
	global_load_dwordx4 v[46:49], v[2:3], off
	global_load_dwordx4 v[42:45], v[2:3], off offset:1024
	global_load_dwordx4 v[38:41], v[2:3], off offset:2048
	global_load_dwordx4 v[34:37], v[2:3], off offset:3072
	v_lshl_add_u64 v[2:3], v[50:51], 0, s[4:5]
	s_and_b64 s[4:5], s[20:21], exec
	s_cselect_b32 s22, s16, s10
	s_ashr_i32 s23, s22, 31
	s_lshl_b64 s[4:5], s[22:23], 12
	global_load_dwordx4 v[30:33], v[2:3], off
	global_load_dwordx4 v[26:29], v[2:3], off offset:1024
	global_load_dwordx4 v[22:25], v[2:3], off offset:2048
	global_load_dwordx4 v[18:21], v[2:3], off offset:3072
	v_lshl_add_u64 v[2:3], v[50:51], 0, s[4:5]
	global_load_dwordx4 v[14:17], v[2:3], off
	global_load_dwordx4 v[10:13], v[2:3], off offset:1024
	global_load_dwordx4 v[6:9], v[2:3], off offset:2048
	s_nop 0
	global_load_dwordx4 v[2:5], v[2:3], off offset:3072
	s_lshl_b64 s[4:5], s[10:11], 11
	v_lshl_add_u64 v[72:73], v[52:53], 0, s[4:5]
	s_waitcnt vmcnt(15)
	v_mul_f32_e32 v1, v57, v57
	v_mul_f32_e32 v82, v59, v59
	v_cvt_pk_bf16_f32 v74, v56, v57
	v_cvt_pk_bf16_f32 v75, v58, v59
	s_waitcnt vmcnt(14)
	v_mul_f32_e32 v57, v61, v61
	v_mul_f32_e32 v59, v63, v63
	v_cvt_pk_bf16_f32 v76, v60, v61
	v_cvt_pk_bf16_f32 v77, v62, v63
	s_waitcnt vmcnt(13)
	v_mul_f32_e32 v61, v65, v65
	v_mul_f32_e32 v63, v67, v67
	v_fmac_f32_e32 v1, v56, v56
	v_fmac_f32_e32 v82, v58, v58
	v_fmac_f32_e32 v57, v60, v60
	v_fmac_f32_e32 v59, v62, v62
	v_cvt_pk_bf16_f32 v78, v64, v65
	v_cvt_pk_bf16_f32 v79, v66, v67
	s_waitcnt vmcnt(12)
	v_mul_f32_e32 v65, v69, v69
	v_mul_f32_e32 v67, v71, v71
	v_fmac_f32_e32 v61, v64, v64
	v_fmac_f32_e32 v63, v66, v66
	v_add_f32_e32 v1, v1, v82
	v_add_f32_e32 v56, v57, v59
	v_fmac_f32_e32 v65, v68, v68
	v_fmac_f32_e32 v67, v70, v70
	v_add_f32_e32 v57, v61, v63
	v_add_f32_e32 v1, v1, v56
	v_add_f32_e32 v58, v65, v67
	v_add_f32_e32 v1, v1, v57
	v_add_f32_e32 v1, v1, v58
	v_mov_b32_e32 v56, v1
	v_cvt_pk_bf16_f32 v80, v68, v69
	v_cvt_pk_bf16_f32 v81, v70, v71
	v_mov_b32_dpp v56, v56 quad_perm:[1,0,3,2] row_mask:0xf bank_mask:0xf
	v_add_f32_e32 v1, v1, v56
	v_mov_b32_e32 v56, v1
	global_store_dwordx2 v[72:73], v[74:75], off
	global_store_dwordx2 v[72:73], v[76:77], off offset:512
	v_mov_b32_dpp v56, v56 quad_perm:[2,3,0,1] row_mask:0xf bank_mask:0xf
	v_add_f32_e32 v1, v1, v56
	v_mov_b32_e32 v56, v1
	global_store_dwordx2 v[72:73], v[78:79], off offset:1024
	global_store_dwordx2 v[72:73], v[80:81], off offset:1536
	v_mov_b32_dpp v56, v56 row_half_mirror row_mask:0xf bank_mask:0xf
	v_add_f32_e32 v1, v1, v56
	s_nop 1
	v_add_f32_dpp v1, v1, v1 row_mirror row_mask:0xf bank_mask:0xf
	s_nop 0
	v_readlane_b32 s60, v1, 0
	v_readlane_b32 s3, v1, 16
	v_readlane_b32 s61, v1, 32
	v_readlane_b32 s4, v1, 48
	s_and_saveexec_b64 s[56:57], s[6:7]
	s_cbranch_execz .LBB0_158
	v_mov_b32_e32 v58, s3
	v_mov_b32_e32 v59, s4
	v_pk_add_f32 v[58:59], s[60:61], v[58:59]
	s_lshl_b64 s[10:11], s[10:11], 6
	v_add_f32_e32 v1, v58, v59
	v_lshl_add_u64 v[56:57], v[54:55], 0, s[10:11]
	v_cndmask_b32_e64 v1, 0, v1, s[8:9]
	global_store_dword v[56:57], v1, off

; __device__ __forceinline__ unsigned pk2(float lo, float hi) { const f32x2 v = {lo, hi}; const bf16x2_t b = __builtin_convertvector(v, bf16x2_t); return __builtin_bit_cast(unsigned, b); }
; __device__ __forceinline__ void phase0(const Ctx& C) {
;     ...
;         for (int r = 0; r < 4; ++r) {
;             const int rw = row + r * NGW; const bool has = rw < T_;
;             float s = 0.f; u32x2* oa = (u32x2*)(xb + (size_t)(has ? rw : row) * D_) + lane;
; #pragma unroll
;             for (int j = 0; j < 4; ++j) {
;                 s += (v[r][j][0] * v[r][j][0] + v[r][j][1] * v[r][j][1]) + (v[r][j][2] * v[r][j][2] + v[r][j][3] * v[r][j][3]);
;                 if (has) { u32x2 w; w.x = pk2(v[r][j][0], v[r][j][1]); w.y = pk2(v[r][j][2], v[r][j][3]); oa[64 * j] = w; }
;             }
;             s = wave_sum(s);
;             if (has && lane < 16) ssq[(size_t)rw * 16 + lane] = lane == 0 ? s : 0.f;
.LBB0_163:
	s_waitcnt vmcnt(15)
	v_mul_f32_e32 v1, v47, v47
	s_waitcnt vmcnt(14)
	v_mul_f32_e32 v43, v43, v43
	v_fmac_f32_e32 v1, v46, v46
	v_mul_f32_e32 v46, v49, v49
	v_fmac_f32_e32 v43, v42, v42
	v_mul_f32_e32 v42, v45, v45
	s_waitcnt vmcnt(13)
	v_mul_f32_e32 v39, v39, v39
	v_fmac_f32_e32 v46, v48, v48
	v_fmac_f32_e32 v42, v44, v44
	v_fmac_f32_e32 v39, v38, v38
	v_mul_f32_e32 v38, v41, v41
	s_waitcnt vmcnt(12)
	v_mul_f32_e32 v35, v35, v35
	v_add_f32_e32 v1, v1, v46
	v_add_f32_e32 v42, v43, v42
	v_fmac_f32_e32 v38, v40, v40
	v_fmac_f32_e32 v35, v34, v34
	v_mul_f32_e32 v34, v37, v37
	v_add_f32_e32 v1, v1, v42
	v_add_f32_e32 v38, v39, v38
	v_fmac_f32_e32 v34, v36, v36
	v_add_f32_e32 v1, v1, v38
	v_add_f32_e32 v34, v35, v34
	v_add_f32_e32 v1, v1, v34
	s_nop 1
	v_add_f32_dpp v1, v1, v1 quad_perm:[1,0,3,2] row_mask:0xf bank_mask:0xf
	s_nop 1
	v_add_f32_dpp v1, v1, v1 quad_perm:[2,3,0,1] row_mask:0xf bank_mask:0xf
	s_nop 1
	v_add_f32_dpp v1, v1, v1 row_half_mirror row_mask:0xf bank_mask:0xf
	s_nop 1
	v_add_f32_dpp v1, v1, v1 row_mirror row_mask:0xf bank_mask:0xf
	s_nop 0
	v_readlane_b32 s44, v1, 0
	v_readlane_b32 s3, v1, 16
	v_readlane_b32 s45, v1, 32
	v_readlane_b32 s4, v1, 48
	s_and_saveexec_b64 s[42:43], s[10:11]
	s_cbranch_execz .LBB0_165
	v_mov_b32_e32 v36, s3
	v_mov_b32_e32 v37, s4
	s_ashr_i32 s15, s14, 31
	v_pk_add_f32 v[36:37], s[44:45], v[36:37]
	s_lshl_b64 s[10:11], s[14:15], 6
	v_add_f32_e32 v1, v36, v37
	v_lshl_add_u64 v[34:35], v[54:55], 0, s[10:11]
	v_cndmask_b32_e64 v1, 0, v1, s[8:9]
	global_store_dword v[34:35], v1, off

; __device__ __forceinline__ unsigned pk2(float lo, float hi) { const f32x2 v = {lo, hi}; const bf16x2_t b = __builtin_convertvector(v, bf16x2_t); return __builtin_bit_cast(unsigned, b); }
; __device__ __forceinline__ void phase0(const Ctx& C) {
;     ...
;         for (int r = 0; r < 4; ++r) {
;             const int rw = row + r * NGW; const bool has = rw < T_;
;             float s = 0.f; u32x2* oa = (u32x2*)(xb + (size_t)(has ? rw : row) * D_) + lane;
; #pragma unroll
;             for (int j = 0; j < 4; ++j) {
;                 s += (v[r][j][0] * v[r][j][0] + v[r][j][1] * v[r][j][1]) + (v[r][j][2] * v[r][j][2] + v[r][j][3] * v[r][j][3]);
;                 if (has) { u32x2 w; w.x = pk2(v[r][j][0], v[r][j][1]); w.y = pk2(v[r][j][2], v[r][j][3]); oa[64 * j] = w; }
;             }
;             s = wave_sum(s);
;             if (has && lane < 16) ssq[(size_t)rw * 16 + lane] = lane == 0 ? s : 0.f;
.LBB0_170:
	s_waitcnt vmcnt(11)
	v_mul_f32_e32 v1, v31, v31
	s_waitcnt vmcnt(10)
	v_mul_f32_e32 v27, v27, v27
	v_fmac_f32_e32 v1, v30, v30
	v_mul_f32_e32 v30, v33, v33
	v_fmac_f32_e32 v27, v26, v26
	v_mul_f32_e32 v26, v29, v29
	s_waitcnt vmcnt(9)
	v_mul_f32_e32 v23, v23, v23
	v_fmac_f32_e32 v30, v32, v32
	v_fmac_f32_e32 v26, v28, v28
	v_fmac_f32_e32 v23, v22, v22
	v_mul_f32_e32 v22, v25, v25
	s_waitcnt vmcnt(8)
	v_mul_f32_e32 v19, v19, v19
	v_add_f32_e32 v1, v1, v30
	v_add_f32_e32 v26, v27, v26
	v_fmac_f32_e32 v22, v24, v24
	v_fmac_f32_e32 v19, v18, v18
	v_mul_f32_e32 v18, v21, v21
	v_add_f32_e32 v1, v1, v26
	v_add_f32_e32 v22, v23, v22
	v_fmac_f32_e32 v18, v20, v20
	v_add_f32_e32 v1, v1, v22
	v_add_f32_e32 v18, v19, v18
	v_add_f32_e32 v1, v1, v18
	s_nop 1
	v_add_f32_dpp v1, v1, v1 quad_perm:[1,0,3,2] row_mask:0xf bank_mask:0xf
	s_nop 1
	v_add_f32_dpp v1, v1, v1 quad_perm:[2,3,0,1] row_mask:0xf bank_mask:0xf
	s_nop 1
	v_add_f32_dpp v1, v1, v1 row_half_mirror row_mask:0xf bank_mask:0xf
	s_nop 1
	v_add_f32_dpp v1, v1, v1 row_mirror row_mask:0xf bank_mask:0xf
	s_nop 0
	v_readlane_b32 s40, v1, 0
	v_readlane_b32 s3, v1, 16
	v_readlane_b32 s41, v1, 32
	v_readlane_b32 s4, v1, 48
	s_and_saveexec_b64 s[36:37], s[10:11]
	s_cbranch_execz .LBB0_172
	v_mov_b32_e32 v20, s3
	v_mov_b32_e32 v21, s4
	s_ashr_i32 s19, s18, 31
	v_pk_add_f32 v[20:21], s[40:41], v[20:21]
	s_lshl_b64 s[10:11], s[18:19], 6
	v_add_f32_e32 v1, v20, v21
	v_lshl_add_u64 v[18:19], v[54:55], 0, s[10:11]
	v_cndmask_b32_e64 v1, 0, v1, s[8:9]
	global_store_dword v[18:19], v1, off

; __device__ __forceinline__ unsigned pk2(float lo, float hi) { const f32x2 v = {lo, hi}; const bf16x2_t b = __builtin_convertvector(v, bf16x2_t); return __builtin_bit_cast(unsigned, b); }
; __device__ __forceinline__ void phase0(const Ctx& C) {
;     ...
;         for (int r = 0; r < 4; ++r) {
;             const int rw = row + r * NGW; const bool has = rw < T_;
;             float s = 0.f; u32x2* oa = (u32x2*)(xb + (size_t)(has ? rw : row) * D_) + lane;
; #pragma unroll
;             for (int j = 0; j < 4; ++j) {
;                 s += (v[r][j][0] * v[r][j][0] + v[r][j][1] * v[r][j][1]) + (v[r][j][2] * v[r][j][2] + v[r][j][3] * v[r][j][3]);
;                 if (has) { u32x2 w; w.x = pk2(v[r][j][0], v[r][j][1]); w.y = pk2(v[r][j][2], v[r][j][3]); oa[64 * j] = w; }
;             }
;             s = wave_sum(s);
;             if (has && lane < 16) ssq[(size_t)rw * 16 + lane] = lane == 0 ? s : 0.f;
.LBB0_178:
	s_waitcnt vmcnt(7)
	v_mul_f32_e32 v1, v15, v15
	s_waitcnt vmcnt(6)
	v_mul_f32_e32 v11, v11, v11
	v_fmac_f32_e32 v1, v14, v14
	v_mul_f32_e32 v14, v17, v17
	v_fmac_f32_e32 v11, v10, v10
	v_mul_f32_e32 v10, v13, v13
	s_waitcnt vmcnt(5)
	v_mul_f32_e32 v7, v7, v7
	v_fmac_f32_e32 v14, v16, v16
	v_fmac_f32_e32 v10, v12, v12
	v_fmac_f32_e32 v7, v6, v6
	v_mul_f32_e32 v6, v9, v9
	s_waitcnt vmcnt(4)
	v_mul_f32_e32 v3, v3, v3
	v_add_f32_e32 v1, v1, v14
	v_add_f32_e32 v10, v11, v10
	v_fmac_f32_e32 v6, v8, v8
	v_fmac_f32_e32 v3, v2, v2
	v_mul_f32_e32 v2, v5, v5
	v_add_f32_e32 v1, v1, v10
	v_add_f32_e32 v6, v7, v6
	v_fmac_f32_e32 v2, v4, v4
	v_add_f32_e32 v1, v1, v6
	v_add_f32_e32 v2, v3, v2
	v_add_f32_e32 v1, v1, v2
	s_nop 1
	v_add_f32_dpp v1, v1, v1 quad_perm:[1,0,3,2] row_mask:0xf bank_mask:0xf
	s_nop 1
	v_add_f32_dpp v1, v1, v1 quad_perm:[2,3,0,1] row_mask:0xf bank_mask:0xf
	s_nop 1
	v_add_f32_dpp v1, v1, v1 row_half_mirror row_mask:0xf bank_mask:0xf
	s_nop 1
	v_add_f32_dpp v1, v1, v1 row_mirror row_mask:0xf bank_mask:0xf
	s_nop 0
	v_readlane_b32 s20, v1, 0
	v_readlane_b32 s3, v1, 16
	v_readlane_b32 s21, v1, 32
	v_readlane_b32 s4, v1, 48
	s_and_saveexec_b64 s[18:19], s[10:11]
	s_cbranch_execz .LBB0_155
	v_mov_b32_e32 v4, s3
	v_mov_b32_e32 v5, s4
	s_ashr_i32 s17, s16, 31
	v_pk_add_f32 v[4:5], s[20:21], v[4:5]
	s_lshl_b64 s[10:11], s[16:17], 6
	v_add_f32_e32 v1, v4, v5
	v_lshl_add_u64 v[2:3], v[54:55], 0, s[10:11]
	v_cndmask_b32_e64 v1, 0, v1, s[8:9]
	global_store_dword v[2:3], v1, off
	s_branch .LBB0_155

; __device__ __forceinline__ bf16_t f2bf(float f) { return (bf16_t)(pk2(f, 0.f) & 0xffffu); }
; __device__ __forceinline__ float sigmoidf_(float x) { return frcp(1.0f + __expf(-x)); }
; __device__ __forceinline__ void rwkv_phase_a(const Ctx& C) {
;     ...
;                     for (int i = 0; i < 2; ++i) { const int row = hn * 64 + nc0 + 16 * i;
;                         Bf[0][ks][i] = *(const bf16x8*)(wdecT + (size_t)row * 64 + ks * 32 + q * 8); Bf[1][ks][i] = *(const bf16x8*)(waaaT + (size_t)row * 64 + ks * 32 + q * 8);
;                         Bf[2][ks][i] = *(const bf16x8*)(wgateT + (size_t)row * 128 + ks * 32 + q * 8); Bf[3][ks][i] = *(const bf16x8*)(wgateT + (size_t)row * 128 + 64 + ks * 32 + q * 8); }
;                 zload9(zr, tokb, hn * 64 + ci, zn[0]); zload9(zr, tokb, 512 + hn * 64 + ci, zn[1]); zload9(zr, tokb, 1024 + hn * 64 + ci, zn[2]);
;             }
; #pragma unroll
;             for (int i = 0; i < 2; ++i) {
;                 const int ch = nc0 + 16 * i; const float w0c = w0[h * 64 + ch], a0c = a0[h * 64 + ch];
; #pragma unroll
;                 for (int j = 0; j < 4; ++j) {
;                     const int t = mt * 16 + 4 * q + j;
;                     FM(0)[t * MS + ch] = -0.60653065971f * sigmoidf_(w0c + aw[i][j]);
;                     FM(1)[t * MS + ch] = sigmoidf_(a0c + aa[i][j]);
;                     Gg[(size_t)(tok0 + t) * GWD_ + h * 64 + ch] = f2bf(ag[i][j]);
;                 }
;             }
;         }
;         __syncthreads();
.LBB0_721:
	v_add_u32_e32 v106, s92, v138
	v_ashrrev_i32_e32 v107, 31, v106
	s_add_u32 s22, s26, s18
	v_add_u32_e32 v108, s93, v138
	v_lshlrev_b64 v[100:101], 10, v[106:107]
	s_addc_u32 s23, s27, s19
	v_ashrrev_i32_e32 v109, 31, v108
	v_lshl_or_b32 v100, v122, 1, v100
	v_add_lshl_u32 v118, s56, v209, 1
	v_add_u32_e32 v110, s94, v138
	v_lshlrev_b64 v[98:99], 10, v[108:109]
	v_lshl_add_u64 v[100:101], s[22:23], 0, v[100:101]
	v_ashrrev_i32_e32 v111, 31, v110
	v_or_b32_e32 v98, v98, v118
	v_add_co_u32_e32 v100, vcc, s6, v100
	v_lshlrev_b64 v[106:107], 10, v[110:111]
	v_lshl_add_u64 v[98:99], s[22:23], 0, v[98:99]
	v_addc_co_u32_e32 v101, vcc, 0, v101, vcc
	v_or_b32_e32 v106, v106, v118
	v_add_co_u32_e32 v98, vcc, s6, v98
	v_lshl_add_u64 v[106:107], s[22:23], 0, v[106:107]
	s_nop 0
	v_addc_co_u32_e32 v99, vcc, 0, v99, vcc
	v_cvt_pk_bf16_f32 v116, v182, s0
	v_cvt_pk_bf16_f32 v117, v183, s0
	v_add_co_u32_e32 v106, vcc, s6, v106
	v_cvt_pk_bf16_f32 v119, v184, s0
	s_nop 0
	v_addc_co_u32_e32 v107, vcc, 0, v107, vcc
	global_store_short v[100:101], v116, off
	global_store_short v[98:99], v117, off
	global_store_short v[106:107], v119, off
	v_lshl_add_u32 v112, v112, 2, 0
	v_cvt_pk_bf16_f32 v120, v185, s0
	v_readlane_b32 s44, v254, 10
	v_readlane_b32 s45, v254, 11
	v_readlane_b32 s48, v254, 14
	v_readlane_b32 s49, v254, 15
	v_readlane_b32 s50, v254, 16
	v_readlane_b32 s51, v254, 17
	s_mov_b64 s[52:53], s[40:41]
	v_readlane_b32 s40, v254, 42
	v_readlane_b32 s41, v254, 43
	s_movk_i32 s14, 0x220
	v_readlane_b32 s46, v254, 48
	v_readlane_b32 s47, v254, 49
	v_readlane_b32 s48, v254, 50
	v_readlane_b32 s44, v254, 46
	v_readlane_b32 s45, v254, 47
	v_readlane_b32 s42, v254, 44
	v_readlane_b32 s43, v254, 45
	v_readlane_b32 s49, v254, 51
	v_readlane_b32 s50, v254, 52
	v_readlane_b32 s51, v254, 53
	v_readlane_b32 s52, v254, 54
	v_readlane_b32 s53, v254, 55
	v_readlane_b32 s54, v254, 56
	v_readlane_b32 s55, v254, 57
	s_waitcnt vmcnt(52)
	v_add_f32_e32 v108, v150, v114
	v_add_f32_e32 v110, v151, v114
	s_waitcnt vmcnt(51)
	v_add_f32_e32 v109, v154, v115
	v_mul_f32_e32 v108, 0xbfb8aa3b, v108
	v_mul_f32_e32 v109, 0xbfb8aa3b, v109
	v_mul_f32_e32 v110, 0xbfb8aa3b, v110
	v_exp_f32_e32 v108, v108
	v_exp_f32_e32 v109, v109
	v_exp_f32_e32 v110, v110
	v_add_f32_e32 v111, v155, v115
	v_add_f32_e32 v116, v152, v114
	v_add_f32_e32 v117, v156, v115
	v_mul_f32_e32 v111, 0xbfb8aa3b, v111
	v_mul_f32_e32 v116, 0xbfb8aa3b, v116
	v_mul_f32_e32 v117, 0xbfb8aa3b, v117
	s_waitcnt vmcnt(49)
	v_add_f32_e32 v102, v102, v113
	v_exp_f32_e32 v111, v111
	v_exp_f32_e32 v116, v116
	v_exp_f32_e32 v117, v117
	v_add_f32_e32 v108, 1.0, v108
	v_mul_f32_e32 v102, 0xbfb8aa3b, v102
	v_add_f32_e32 v109, 1.0, v109
	v_add_f32_e32 v110, 1.0, v110
	v_rcp_f32_e32 v108, v108
	v_exp_f32_e32 v102, v102
	v_rcp_f32_e32 v119, v109
	v_rcp_f32_e32 v109, v110
	v_add_f32_e32 v111, 1.0, v111
	v_add_f32_e32 v116, 1.0, v116
	v_add_f32_e32 v117, 1.0, v117
	v_rcp_f32_e32 v110, v111
	v_rcp_f32_e32 v111, v116
	v_rcp_f32_e32 v116, v117
	v_mul_f32_e32 v117, 0xbf1b4598, v108
	v_add_u32_e32 v108, s95, v138
	v_add_f32_e32 v102, 1.0, v102
	v_mul_f32_e32 v124, 0xbf1b4598, v109
	v_ashrrev_i32_e32 v109, 31, v108
	v_rcp_f32_e32 v102, v102
	v_lshlrev_b64 v[108:109], 10, v[108:109]
	v_or_b32_e32 v108, v108, v118
	v_add_f32_e32 v118, v134, v121
	v_mul_f32_e32 v118, 0xbfb8aa3b, v118
	v_add_f32_e32 v103, v103, v113
	v_exp_f32_e32 v118, v118
	v_mul_f32_e32 v102, 0xbf1b4598, v102
	v_mul_f32_e32 v103, 0xbfb8aa3b, v103
	ds_write2_b32 v112, v117, v102 offset1:16
	v_exp_f32_e32 v103, v103
	v_add_f32_e32 v117, v135, v121
	v_mul_f32_e32 v117, 0xbfb8aa3b, v117
	v_exp_f32_e32 v117, v117
	v_add_f32_e32 v118, 1.0, v118
	v_rcp_f32_e32 v118, v118
	v_add_f32_e32 v103, 1.0, v103
	v_rcp_f32_e32 v103, v103
	v_lshl_add_u64 v[108:109], s[22:23], 0, v[108:109]
	v_add_f32_e32 v117, 1.0, v117
	v_add_co_u32_e32 v108, vcc, s6, v108
	v_add_u32_e32 v102, 0x4400, v112
	v_rcp_f32_e32 v117, v117
	v_addc_co_u32_e32 v109, vcc, 0, v109, vcc
	ds_write2_b32 v102, v119, v118 offset1:16
	v_cvt_pk_bf16_f32 v118, v146, s0
	global_store_short v[108:109], v120, off
	global_store_short v[100:101], v118, off offset:32
	v_mul_f32_e32 v100, 0xbf1b4598, v103
	ds_write2_b32 v112, v124, v100 offset0:68 offset1:84
	ds_write2_b32 v102, v110, v117 offset0:68 offset1:84
	v_add_f32_e32 v100, v104, v113
	v_mul_f32_e32 v100, 0xbfb8aa3b, v100
	v_exp_f32_e32 v100, v100
	v_add_f32_e32 v101, v136, v121
	v_mul_f32_e32 v101, 0xbfb8aa3b, v101
	v_exp_f32_e32 v101, v101
	v_add_f32_e32 v100, 1.0, v100
	v_rcp_f32_e32 v100, v100
	v_cvt_pk_bf16_f32 v103, v147, s0
	v_add_f32_e32 v101, 1.0, v101
	v_rcp_f32_e32 v101, v101
	v_mul_f32_e32 v111, 0xbf1b4598, v111
	global_store_short v[98:99], v103, off offset:32
	v_mul_f32_e32 v98, 0xbf1b4598, v100
	v_add_f32_e32 v114, v153, v114
	ds_write2_b32 v112, v111, v98 offset0:136 offset1:152
	ds_write2_b32 v102, v116, v101 offset0:136 offset1:152
	v_add_f32_e32 v98, v105, v113
	v_mul_f32_e32 v114, 0xbfb8aa3b, v114
	v_mul_f32_e32 v98, 0xbfb8aa3b, v98
	v_add_f32_e32 v115, v157, v115
	v_exp_f32_e32 v114, v114
	v_exp_f32_e32 v98, v98
	v_add_f32_e32 v99, v137, v121
	v_mul_f32_e32 v115, 0xbfb8aa3b, v115
	v_mul_f32_e32 v99, 0xbfb8aa3b, v99
	v_exp_f32_e32 v115, v115
	v_exp_f32_e32 v99, v99
	v_add_f32_e32 v114, 1.0, v114
	v_add_f32_e32 v98, 1.0, v98
	v_rcp_f32_e32 v114, v114
	v_rcp_f32_e32 v98, v98
	v_add_f32_e32 v115, 1.0, v115
	v_add_f32_e32 v99, 1.0, v99
	v_rcp_f32_e32 v115, v115
	v_rcp_f32_e32 v99, v99
	v_mul_f32_e32 v114, 0xbf1b4598, v114
	v_cvt_pk_bf16_f32 v100, v148, s0
	v_mul_f32_e32 v98, 0xbf1b4598, v98
	global_store_short v[106:107], v100, off offset:32
	ds_write2_b32 v112, v114, v98 offset0:204 offset1:220
	ds_write2_b32 v102, v115, v99 offset0:204 offset1:220
	v_cvt_pk_bf16_f32 v98, v149, s0
	global_store_short v[108:109], v98, off offset:32
	v_lshlrev_b64 v[98:99], 2, v[188:189]
	v_lshl_add_u64 v[100:101], s[64:65], 0, v[98:99]
	s_waitcnt lgkmcnt(0)
	s_barrier
; __device__ __forceinline__ void rwkv_phase_a(const Ctx& C) {
;     ...
;             for (int u = 0; u < 8; ++u) {
;                 const int t = tg8 * 8 + u;
;                 ld[u] = FM(0)[t * MS + ci]; av[u] = FM(1)[t * MS + ci];
;                 const float kr = kx[u] * kkc; const float n2 = wave_sum(kr * kr);
;                 kkv[u] = kr * __builtin_amdgcn_rsqf(fmaxf(n2, 1e-24f));
;                 k2[u] = kx[u] * (1.0f + (av[u] - 1.0f) * kac);
;                 const float bs = wave_sum(rr[u] * k2[u] * rkc);
;                 if (lane == 0) bon[(size_t)(tok0 + t) * 8 + h] = bs;
;                 run += ld[u]; cl[u] = run;
	s_waitcnt vmcnt(51)
	v_lshl_add_u64 v[100:101], s[66:67], 0, v[98:99]
	v_mov_b32_e32 v125, v126
	v_lshl_add_u64 v[98:99], s[40:41], 0, v[98:99]
	v_mov_b32_e32 v117, v127
	v_mov_b32_e32 v124, v128
	v_cmp_lt_i32_e32 vcc, 0, v230
	v_lshlrev_b32_e32 v98, 16, v229
	v_and_b32_e32 v99, 0xffff0000, v229
	v_cndmask_b32_e64 v126, 0, 1.0, vcc
	v_fma_f32 v98, v126, v98, -v99
	v_fma_f32 v137, v223, v98, v99
	v_and_b32_e32 v98, 0xffff0000, v219
	v_lshlrev_b32_e32 v102, 16, v228
	v_fma_f32 v98, v126, v98, -v102
	v_fma_f32 v98, v222, v98, v102
	v_mad_u64_u32 v[100:101], s[14:15], v216, s14, v[192:193]
	v_lshl_add_u32 v100, v100, 2, 0
	ds_read2st64_b32 v[100:101], v100 offset1:68
	v_cmp_eq_u32_e32 vcc, 0, v192
	s_nop 0
	v_mul_f32_e32 v127, v98, v125
	v_mul_f32_e32 v103, v127, v127
	s_nop 1
	v_mov_b32_dpp v103, v103 quad_perm:[1,0,3,2] row_mask:0xf bank_mask:0xf
	v_fmac_f32_e32 v103, v127, v127
	s_nop 1
	v_add_f32_dpp v103, v103, v103 quad_perm:[2,3,0,1] row_mask:0xf bank_mask:0xf
	s_nop 1
	v_add_f32_dpp v103, v103, v103 row_half_mirror row_mask:0xf bank_mask:0xf
	s_nop 1
	v_add_f32_dpp v103, v103, v103 row_mirror row_mask:0xf bank_mask:0xf
	s_nop 0
	v_readlane_b32 s21, v103, 0
	v_readlane_b32 s47, v103, 16
	v_readlane_b32 s46, v103, 32
	v_readlane_b32 s48, v103, 48
	s_waitcnt lgkmcnt(0)
	v_add_f32_e32 v103, -1.0, v101
	s_nop 0
	v_fma_f32 v103, v117, v103, 1.0
	v_mul_f32_e32 v98, v98, v103
	v_mul_f32_e32 v103, v137, v98
	s_nop 0
	v_mul_f32_e32 v104, v124, v103
	s_nop 1
	v_mov_b32_dpp v104, v104 quad_perm:[1,0,3,2] row_mask:0xf bank_mask:0xf
	v_fmac_f32_e32 v104, v124, v103
	s_nop 1
	v_add_f32_dpp v103, v104, v104 quad_perm:[2,3,0,1] row_mask:0xf bank_mask:0xf
	s_nop 1
	v_add_f32_dpp v103, v103, v103 row_half_mirror row_mask:0xf bank_mask:0xf
	s_nop 1
	v_add_f32_dpp v103, v103, v103 row_mirror row_mask:0xf bank_mask:0xf
	s_nop 0
	v_readlane_b32 s44, v103, 0
	v_readlane_b32 s14, v103, 16
	v_readlane_b32 s45, v103, 32
	v_readlane_b32 s15, v103, 48
	s_and_saveexec_b64 s[22:23], vcc
	s_cbranch_execz .LBB0_723
	v_add_u32_e32 v104, s31, v212
	v_ashrrev_i32_e32 v105, 31, v104
	s_add_u32 s42, s26, s16
	v_mov_b32_e32 v106, s14
	v_mov_b32_e32 v107, s15
	v_lshlrev_b64 v[104:105], 5, v[104:105]
	s_addc_u32 s43, s27, s17
	v_pk_add_f32 v[106:107], s[44:45], v[106:107]
	v_lshl_add_u64 v[104:105], s[42:43], 0, v[104:105]
	v_add_f32_e32 v103, v106, v107
	global_store_dword v[104:105], v103, off
.LBB0_723:
	s_or_b64 exec, exec, s[22:23]
	v_lshlrev_b32_e32 v103, 16, v227
	v_sub_f32_e32 v99, v99, v103
	v_and_b32_e32 v106, 0xffff0000, v228
	v_fma_f32 v139, v223, v99, v103
	v_sub_f32_e32 v99, v102, v106
	v_fma_f32 v99, v222, v99, v106
	v_mul_f32_e32 v128, v99, v125
	v_mul_f32_e32 v102, v128, v128
	v_or_b32_e32 v140, 1, v212
	v_mad_u64_u32 v[104:105], s[14:15], v140, s97, v[192:193]
	v_mov_b32_dpp v102, v102 quad_perm:[1,0,3,2] row_mask:0xf bank_mask:0xf
	v_fmac_f32_e32 v102, v128, v128
	v_mov_b32_e32 v107, v102
	v_lshl_add_u32 v120, v104, 2, 0
	ds_read2st64_b32 v[104:105], v120 offset1:68
	v_mov_b32_dpp v107, v107 quad_perm:[2,3,0,1] row_mask:0xf bank_mask:0xf
	v_add_f32_e32 v102, v102, v107
	s_nop 1
	v_add_f32_dpp v102, v102, v102 row_half_mirror row_mask:0xf bank_mask:0xf
	s_nop 1
	v_add_f32_dpp v102, v102, v102 row_mirror row_mask:0xf bank_mask:0xf
	s_nop 0
	v_readlane_b32 s49, v102, 0
	v_readlane_b32 s74, v102, 16
	v_readlane_b32 s73, v102, 32
	v_readlane_b32 s75, v102, 48
	s_waitcnt lgkmcnt(0)
	v_add_f32_e32 v102, -1.0, v105
	v_fma_f32 v102, v117, v102, 1.0
	v_mul_f32_e32 v99, v99, v102
	v_mul_f32_e32 v102, v139, v99
	v_mul_f32_e32 v107, v124, v102
	s_nop 1
	v_mov_b32_dpp v107, v107 quad_perm:[1,0,3,2] row_mask:0xf bank_mask:0xf
	v_fmac_f32_e32 v107, v124, v102
	s_nop 1
	v_add_f32_dpp v102, v107, v107 quad_perm:[2,3,0,1] row_mask:0xf bank_mask:0xf
	s_nop 1
	v_add_f32_dpp v102, v102, v102 row_half_mirror row_mask:0xf bank_mask:0xf
	s_nop 1
	v_add_f32_dpp v102, v102, v102 row_mirror row_mask:0xf bank_mask:0xf
	s_nop 0
	v_readlane_b32 s44, v102, 0
	v_readlane_b32 s14, v102, 16
	v_readlane_b32 s45, v102, 32
	v_readlane_b32 s15, v102, 48
	s_and_saveexec_b64 s[22:23], vcc
	s_cbranch_execz .LBB0_725
	v_add_u32_e32 v108, s61, v212
	v_ashrrev_i32_e32 v109, 31, v108
	s_add_u32 s42, s26, s16
	v_mov_b32_e32 v110, s14
	v_mov_b32_e32 v111, s15
	v_lshlrev_b64 v[108:109], 5, v[108:109]
	s_addc_u32 s43, s27, s17
	v_pk_add_f32 v[110:111], s[44:45], v[110:111]
	v_lshl_add_u64 v[108:109], s[42:43], 0, v[108:109]
	v_add_f32_e32 v102, v110, v111
	global_store_dword v[108:109], v102, off
.LBB0_725:
	s_or_b64 exec, exec, s[22:23]
	v_and_b32_e32 v108, 0xffff0000, v227
	v_sub_f32_e32 v102, v103, v108
	v_lshlrev_b32_e32 v103, 16, v226
	v_fma_f32 v141, v223, v102, v108
	v_sub_f32_e32 v102, v106, v103
	v_fma_f32 v102, v222, v102, v103
	v_mul_f32_e32 v129, v102, v125
	v_mul_f32_e32 v109, v129, v129
	v_add_u32_e32 v106, 16, v120
	ds_read2st64_b32 v[106:107], v106 offset0:1 offset1:69
	v_mov_b32_dpp v109, v109 quad_perm:[1,0,3,2] row_mask:0xf bank_mask:0xf
	v_fmac_f32_e32 v109, v129, v129
	s_nop 1
	v_add_f32_dpp v109, v109, v109 quad_perm:[2,3,0,1] row_mask:0xf bank_mask:0xf
	s_nop 1
	v_add_f32_dpp v109, v109, v109 row_half_mirror row_mask:0xf bank_mask:0xf
	s_nop 1
	v_add_f32_dpp v109, v109, v109 row_mirror row_mask:0xf bank_mask:0xf
	s_nop 0
	v_readlane_b32 s76, v109, 0
	v_readlane_b32 s78, v109, 16
	v_readlane_b32 s77, v109, 32
	v_readlane_b32 s79, v109, 48
	s_waitcnt lgkmcnt(0)
	v_add_f32_e32 v109, -1.0, v107
	v_fma_f32 v109, v117, v109, 1.0
	v_mul_f32_e32 v102, v102, v109
	v_mul_f32_e32 v109, v141, v102
	v_mul_f32_e32 v110, v124, v109
	s_nop 1
	v_mov_b32_dpp v110, v110 quad_perm:[1,0,3,2] row_mask:0xf bank_mask:0xf
	v_fmac_f32_e32 v110, v124, v109
	s_nop 1
	v_add_f32_dpp v109, v110, v110 quad_perm:[2,3,0,1] row_mask:0xf bank_mask:0xf
	s_nop 1
	v_add_f32_dpp v109, v109, v109 row_half_mirror row_mask:0xf bank_mask:0xf
	s_nop 1
	v_add_f32_dpp v109, v109, v109 row_mirror row_mask:0xf bank_mask:0xf
	s_nop 0
	v_readlane_b32 s44, v109, 0
	v_readlane_b32 s14, v109, 16
	v_readlane_b32 s45, v109, 32
	v_readlane_b32 s15, v109, 48
	s_and_saveexec_b64 s[22:23], vcc
	s_cbranch_execz .LBB0_727
	v_add_u32_e32 v110, s62, v212
	v_ashrrev_i32_e32 v111, 31, v110
	s_add_u32 s42, s26, s16
	v_mov_b32_e32 v112, s14
	v_mov_b32_e32 v113, s15
	v_lshlrev_b64 v[110:111], 5, v[110:111]
	s_addc_u32 s43, s27, s17
	v_pk_add_f32 v[112:113], s[44:45], v[112:113]
	v_lshl_add_u64 v[110:111], s[42:43], 0, v[110:111]
	v_add_f32_e32 v109, v112, v113
	global_store_dword v[110:111], v109, off
; __device__ __forceinline__ void rwkv_phase_a(const Ctx& C) {
;     ...
;             for (int u = 0; u < 8; ++u) {
;                 const int t = tg8 * 8 + u;
;                 ld[u] = FM(0)[t * MS + ci]; av[u] = FM(1)[t * MS + ci];
;                 const float kr = kx[u] * kkc; const float n2 = wave_sum(kr * kr);
;                 kkv[u] = kr * __builtin_amdgcn_rsqf(fmaxf(n2, 1e-24f));
;                 k2[u] = kx[u] * (1.0f + (av[u] - 1.0f) * kac);
;                 const float bs = wave_sum(rr[u] * k2[u] * rkc);
;                 if (lane == 0) bon[(size_t)(tok0 + t) * 8 + h] = bs;
;                 run += ld[u]; cl[u] = run;
.LBB0_727:
	s_or_b64 exec, exec, s[22:23]
	v_and_b32_e32 v111, 0xffff0000, v226
	v_sub_f32_e32 v103, v103, v111
	v_fma_f32 v103, v222, v103, v111
	v_mul_f32_e32 v130, v103, v125
	v_mul_f32_e32 v112, v130, v130
	v_lshlrev_b32_e32 v110, 16, v225
	v_sub_f32_e32 v108, v108, v110
	v_mov_b32_dpp v112, v112 quad_perm:[1,0,3,2] row_mask:0xf bank_mask:0xf
	v_fmac_f32_e32 v112, v130, v130
	v_mov_b32_e32 v113, v112
	v_fma_f32 v142, v223, v108, v110
	v_add_u32_e32 v108, 32, v120
	v_mov_b32_dpp v113, v113 quad_perm:[2,3,0,1] row_mask:0xf bank_mask:0xf
	v_add_f32_e32 v112, v112, v113
	v_mov_b32_e32 v113, v112
	ds_read2st64_b32 v[108:109], v108 offset0:2 offset1:70
	s_nop 0
	v_mov_b32_dpp v113, v113 row_half_mirror row_mask:0xf bank_mask:0xf
	v_add_f32_e32 v112, v112, v113
	s_nop 1
	v_add_f32_dpp v112, v112, v112 row_mirror row_mask:0xf bank_mask:0xf
	s_nop 0
	v_readlane_b32 s80, v112, 0
	v_readlane_b32 s14, v112, 16
	v_readlane_b32 s81, v112, 32
	v_readlane_b32 s15, v112, 48
	s_waitcnt lgkmcnt(0)
	v_add_f32_e32 v112, -1.0, v109
	v_fma_f32 v112, v117, v112, 1.0
	v_mul_f32_e32 v103, v103, v112
	v_mul_f32_e32 v112, v142, v103
	v_mul_f32_e32 v113, v124, v112
	s_nop 1
	v_mov_b32_dpp v113, v113 quad_perm:[1,0,3,2] row_mask:0xf bank_mask:0xf
	v_fmac_f32_e32 v113, v124, v112
	s_nop 1
	v_add_f32_dpp v112, v113, v113 quad_perm:[2,3,0,1] row_mask:0xf bank_mask:0xf
	s_nop 1
	v_add_f32_dpp v112, v112, v112 row_half_mirror row_mask:0xf bank_mask:0xf
	s_nop 1
	v_add_f32_dpp v112, v112, v112 row_mirror row_mask:0xf bank_mask:0xf
	s_nop 0
	v_readlane_b32 s44, v112, 0
	v_readlane_b32 s42, v112, 16
	v_readlane_b32 s45, v112, 32
	v_readlane_b32 s43, v112, 48
	s_and_saveexec_b64 s[22:23], vcc
	s_cbranch_execz .LBB0_729
	v_add_u32_e32 v112, s63, v212
	v_ashrrev_i32_e32 v113, 31, v112
	s_add_u32 s52, s26, s16
	v_mov_b32_e32 v114, s42
	v_mov_b32_e32 v115, s43
	v_lshlrev_b64 v[112:113], 5, v[112:113]
	s_addc_u32 s53, s27, s17
	v_pk_add_f32 v[114:115], s[44:45], v[114:115]
	v_lshl_add_u64 v[112:113], s[52:53], 0, v[112:113]
	v_add_f32_e32 v114, v114, v115
	global_store_dword v[112:113], v114, off
.LBB0_729:
	s_or_b64 exec, exec, s[22:23]
	v_and_b32_e32 v114, 0xffff0000, v225
	v_sub_f32_e32 v110, v110, v114
	v_lshlrev_b32_e32 v115, 16, v224
	v_fma_f32 v143, v223, v110, v114
	v_sub_f32_e32 v110, v111, v115
	v_fma_f32 v110, v222, v110, v115
	v_add_u32_e32 v111, 48, v120
	v_mul_f32_e32 v131, v110, v125
	ds_read2st64_b32 v[112:113], v111 offset0:3 offset1:71
	v_mul_f32_e32 v111, v131, v131
	s_nop 1
	v_mov_b32_dpp v111, v111 quad_perm:[1,0,3,2] row_mask:0xf bank_mask:0xf
	v_fmac_f32_e32 v111, v131, v131
	s_nop 1
	v_add_f32_dpp v111, v111, v111 quad_perm:[2,3,0,1] row_mask:0xf bank_mask:0xf
	s_nop 1
	v_add_f32_dpp v111, v111, v111 row_half_mirror row_mask:0xf bank_mask:0xf
	s_nop 1
	v_add_f32_dpp v111, v111, v111 row_mirror row_mask:0xf bank_mask:0xf
	s_nop 0
	v_readlane_b32 s88, v111, 0
	v_readlane_b32 s42, v111, 16
	v_readlane_b32 s89, v111, 32
	v_readlane_b32 s43, v111, 48
	s_waitcnt lgkmcnt(0)
	v_add_f32_e32 v111, -1.0, v113
	v_fma_f32 v111, v117, v111, 1.0
	v_mul_f32_e32 v110, v110, v111
	v_mul_f32_e32 v111, v143, v110
	v_mul_f32_e32 v116, v124, v111
	s_nop 1
	v_mov_b32_dpp v116, v116 quad_perm:[1,0,3,2] row_mask:0xf bank_mask:0xf
	v_fmac_f32_e32 v116, v124, v111
	s_nop 1
	v_add_f32_dpp v111, v116, v116 quad_perm:[2,3,0,1] row_mask:0xf bank_mask:0xf
	s_nop 1
	v_add_f32_dpp v111, v111, v111 row_half_mirror row_mask:0xf bank_mask:0xf
	s_nop 1
	v_add_f32_dpp v111, v111, v111 row_mirror row_mask:0xf bank_mask:0xf
	s_nop 0
	v_readlane_b32 s44, v111, 0
	v_readlane_b32 s52, v111, 16
	v_readlane_b32 s45, v111, 32
	v_readlane_b32 s53, v111, 48
	s_and_saveexec_b64 s[22:23], vcc
	s_cbranch_execz .LBB0_731
	v_add_u32_e32 v118, s82, v212
	v_ashrrev_i32_e32 v119, 31, v118
	s_add_u32 s54, s26, s16
	v_mov_b32_e32 v132, s52
	v_mov_b32_e32 v133, s53
	v_lshlrev_b64 v[118:119], 5, v[118:119]
	s_addc_u32 s55, s27, s17
	v_pk_add_f32 v[132:133], s[44:45], v[132:133]
	v_lshl_add_u64 v[118:119], s[54:55], 0, v[118:119]
	v_add_f32_e32 v111, v132, v133
	global_store_dword v[118:119], v111, off
; __device__ __forceinline__ void rwkv_phase_a(const Ctx& C) {
;     ...
;             for (int u = 0; u < 8; ++u) {
;                 const int t = tg8 * 8 + u;
;                 ld[u] = FM(0)[t * MS + ci]; av[u] = FM(1)[t * MS + ci];
;                 const float kr = kx[u] * kkc; const float n2 = wave_sum(kr * kr);
;                 kkv[u] = kr * __builtin_amdgcn_rsqf(fmaxf(n2, 1e-24f));
;                 k2[u] = kx[u] * (1.0f + (av[u] - 1.0f) * kac);
;                 const float bs = wave_sum(rr[u] * k2[u] * rkc);
;                 if (lane == 0) bon[(size_t)(tok0 + t) * 8 + h] = bs;
;                 run += ld[u]; cl[u] = run;
.LBB0_731:
	s_or_b64 exec, exec, s[22:23]
	v_lshlrev_b32_e32 v116, 16, v221
	v_sub_f32_e32 v111, v114, v116
	v_and_b32_e32 v118, 0xffff0000, v224
	v_fma_f32 v144, v223, v111, v116
	v_sub_f32_e32 v111, v115, v118
	v_fma_f32 v111, v222, v111, v118
	v_mul_f32_e32 v132, v111, v125
	v_mul_f32_e32 v119, v132, v132
	v_add_u32_e32 v114, 64, v120
	ds_read2st64_b32 v[114:115], v114 offset0:4 offset1:72
	v_mov_b32_dpp v119, v119 quad_perm:[1,0,3,2] row_mask:0xf bank_mask:0xf
	v_fmac_f32_e32 v119, v132, v132
	s_nop 1
	v_add_f32_dpp v119, v119, v119 quad_perm:[2,3,0,1] row_mask:0xf bank_mask:0xf
	s_nop 1
	v_add_f32_dpp v119, v119, v119 row_half_mirror row_mask:0xf bank_mask:0xf
	s_nop 1
	v_add_f32_dpp v119, v119, v119 row_mirror row_mask:0xf bank_mask:0xf
	s_nop 0
	v_readlane_b32 s90, v119, 0
	v_readlane_b32 s60, v119, 16
	v_readlane_b32 s70, v119, 32
	v_readlane_b32 s52, v119, 48
	s_waitcnt lgkmcnt(0)
	v_add_f32_e32 v119, -1.0, v115
	v_fma_f32 v119, v117, v119, 1.0
	v_mul_f32_e32 v111, v111, v119
	v_mul_f32_e32 v119, v144, v111
	v_mul_f32_e32 v121, v124, v119
	s_nop 1
	v_mov_b32_dpp v121, v121 quad_perm:[1,0,3,2] row_mask:0xf bank_mask:0xf
	v_fmac_f32_e32 v121, v124, v119
	s_nop 1
	v_add_f32_dpp v119, v121, v121 quad_perm:[2,3,0,1] row_mask:0xf bank_mask:0xf
	s_nop 1
	v_add_f32_dpp v119, v119, v119 row_half_mirror row_mask:0xf bank_mask:0xf
	s_nop 1
	v_add_f32_dpp v119, v119, v119 row_mirror row_mask:0xf bank_mask:0xf
	s_nop 0
	v_readlane_b32 s44, v119, 0
	v_readlane_b32 s53, v119, 16
	v_readlane_b32 s45, v119, 32
	v_readlane_b32 s54, v119, 48
	s_and_saveexec_b64 s[22:23], vcc
	s_cbranch_execz .LBB0_733
	v_add_u32_e32 v134, s83, v212
	v_ashrrev_i32_e32 v135, 31, v134
	s_add_u32 s58, s26, s16
	v_mov_b32_e32 v146, s53
	v_mov_b32_e32 v147, s54
	v_lshlrev_b64 v[134:135], 5, v[134:135]
	s_addc_u32 s59, s27, s17
	v_pk_add_f32 v[146:147], s[44:45], v[146:147]
	v_lshl_add_u64 v[134:135], s[58:59], 0, v[134:135]
	v_add_f32_e32 v119, v146, v147
	global_store_dword v[134:135], v119, off
.LBB0_733:
	s_or_b64 exec, exec, s[22:23]
	v_and_b32_e32 v134, 0xffff0000, v221
	v_sub_f32_e32 v116, v116, v134
	v_lshlrev_b32_e32 v121, 16, v220
	v_fma_f32 v145, v223, v116, v134
	v_sub_f32_e32 v116, v118, v121
	v_fma_f32 v116, v222, v116, v121
	v_mul_f32_e32 v133, v116, v125
	v_mul_f32_e32 v135, v133, v133
	v_add_u32_e32 v118, 0x50, v120
	ds_read2st64_b32 v[118:119], v118 offset0:5 offset1:73
	v_mov_b32_dpp v135, v135 quad_perm:[1,0,3,2] row_mask:0xf bank_mask:0xf
	v_fmac_f32_e32 v135, v133, v133
	s_nop 1
	v_add_f32_dpp v135, v135, v135 quad_perm:[2,3,0,1] row_mask:0xf bank_mask:0xf
	s_nop 1
	v_add_f32_dpp v135, v135, v135 row_half_mirror row_mask:0xf bank_mask:0xf
	s_nop 1
	v_add_f32_dpp v135, v135, v135 row_mirror row_mask:0xf bank_mask:0xf
	s_nop 0
	v_readlane_b32 s53, v135, 0
	v_readlane_b32 s55, v135, 16
	v_readlane_b32 s54, v135, 32
	v_readlane_b32 s58, v135, 48
	s_waitcnt lgkmcnt(0)
	v_add_f32_e32 v135, -1.0, v119
	v_fma_f32 v135, v117, v135, 1.0
	v_mul_f32_e32 v116, v116, v135
	v_mul_f32_e32 v135, v145, v116
	v_mul_f32_e32 v136, v124, v135
	s_nop 1
	v_mov_b32_dpp v136, v136 quad_perm:[1,0,3,2] row_mask:0xf bank_mask:0xf
	v_fmac_f32_e32 v136, v124, v135
	s_nop 1
	v_add_f32_dpp v135, v136, v136 quad_perm:[2,3,0,1] row_mask:0xf bank_mask:0xf
	s_nop 1
	v_add_f32_dpp v135, v135, v135 row_half_mirror row_mask:0xf bank_mask:0xf
	s_nop 1
	v_add_f32_dpp v135, v135, v135 row_mirror row_mask:0xf bank_mask:0xf
	s_nop 0
	v_readlane_b32 s44, v135, 0
	v_readlane_b32 s59, v135, 16
	v_readlane_b32 s45, v135, 32
	v_readlane_b32 s64, v135, 48
	s_and_saveexec_b64 s[22:23], vcc
	s_cbranch_execz .LBB0_735
	v_add_u32_e32 v146, s10, v212
	v_ashrrev_i32_e32 v147, 31, v146
	s_add_u32 s66, s26, s16
	v_mov_b32_e32 v148, s59
	v_mov_b32_e32 v149, s64
	v_lshlrev_b64 v[146:147], 5, v[146:147]
	s_addc_u32 s67, s27, s17
	v_pk_add_f32 v[148:149], s[44:45], v[148:149]
	v_lshl_add_u64 v[146:147], s[66:67], 0, v[146:147]
	v_add_f32_e32 v135, v148, v149
	global_store_dword v[146:147], v135, off
.LBB0_735:
	s_or_b64 exec, exec, s[22:23]
	v_lshlrev_b32_e32 v146, 16, v219
	v_sub_f32_e32 v134, v134, v146
	v_fmac_f32_e32 v146, v223, v134
	v_and_b32_e32 v134, 0xffff0000, v220
	v_sub_f32_e32 v121, v121, v134
	v_fmac_f32_e32 v134, v222, v121
	v_mul_f32_e32 v125, v134, v125
	v_mul_f32_e32 v135, v125, v125
	v_add_u32_e32 v120, 0x60, v120
	ds_read2st64_b32 v[120:121], v120 offset0:6 offset1:74
	v_mov_b32_dpp v135, v135 quad_perm:[1,0,3,2] row_mask:0xf bank_mask:0xf
	v_fmac_f32_e32 v135, v125, v125
	s_nop 1
	v_add_f32_dpp v135, v135, v135 quad_perm:[2,3,0,1] row_mask:0xf bank_mask:0xf
	s_nop 1
	v_add_f32_dpp v135, v135, v135 row_half_mirror row_mask:0xf bank_mask:0xf
	s_nop 1
	v_add_f32_dpp v135, v135, v135 row_mirror row_mask:0xf bank_mask:0xf
	s_nop 0
	v_readlane_b32 s59, v135, 0
	v_readlane_b32 s65, v135, 16
	v_readlane_b32 s64, v135, 32
	v_readlane_b32 s66, v135, 48
	s_waitcnt lgkmcnt(0)
	v_add_f32_e32 v135, -1.0, v121
	v_fma_f32 v117, v117, v135, 1.0
	v_mul_f32_e32 v117, v134, v117
	v_mul_f32_e32 v134, v146, v117
	v_mul_f32_e32 v135, v124, v134
	s_nop 1
	v_mov_b32_dpp v135, v135 quad_perm:[1,0,3,2] row_mask:0xf bank_mask:0xf
	v_fmac_f32_e32 v135, v124, v134
	s_nop 1
	v_add_f32_dpp v124, v135, v135 quad_perm:[2,3,0,1] row_mask:0xf bank_mask:0xf
	s_nop 1
	v_add_f32_dpp v124, v124, v124 row_half_mirror row_mask:0xf bank_mask:0xf
	s_nop 1
	v_add_f32_dpp v124, v124, v124 row_mirror row_mask:0xf bank_mask:0xf
	s_nop 0
	v_readlane_b32 s44, v124, 0
	v_readlane_b32 s67, v124, 16
	v_readlane_b32 s45, v124, 32
	v_readlane_b32 s96, v124, 48
	s_and_saveexec_b64 s[22:23], vcc
	s_cbranch_execz .LBB0_737
	v_add_u32_e32 v134, s11, v212
	v_ashrrev_i32_e32 v135, 31, v134
	s_add_u32 vcc_lo, s26, s16
	v_mov_b32_e32 v148, s67
	v_mov_b32_e32 v149, s96
	v_lshlrev_b64 v[134:135], 5, v[134:135]
	s_addc_u32 vcc_hi, s27, s17
	v_pk_add_f32 v[148:149], s[44:45], v[148:149]
	v_lshl_add_u64 v[134:135], vcc, 0, v[134:135]
	v_add_f32_e32 v124, v148, v149
	global_store_dword v[134:135], v124, off

; __device__ __forceinline__ void rwkv_phase_c(const Ctx& C) {
;     ...
;             for (int u = 0; u < 8; ++u) { const int tok = tok0 + tg8 * 8 + u; vv[u] = zshift(zr, tok, 1024 + h * 64 + ci, muv); bo[u] = bon[(size_t)tok * 8 + h]; gt[u] = bf2f(Gg[(size_t)tok * GWD_ + h * 64 + ci]); }
;             f32x4 xy[2], xs[2]; ZACC(xy); ZACC(xs);
; #pragma unroll
;             for (int ks = 0; ks < 2; ++ks) {
;                 const bf16x8 a = *(const LAS bf16x8*)(Rb + mrow * BS + ks * 32 + q * 8);
;                 const bf16x8 h0 = *(const LAS bf16x8*)(SH + nc0 * BS + ks * 32 + q * 8), h1 = *(const LAS bf16x8*)(SH + (nc0 + 16) * BS + ks * 32 + q * 8);
;                 const bf16x8 l0 = *(const LAS bf16x8*)(SL + nc0 * BS + ks * 32 + q * 8), l1 = *(const LAS bf16x8*)(SL + (nc0 + 16) * BS + ks * 32 + q * 8);
;                 xy[0] = __builtin_amdgcn_mfma_f32_16x16x32_bf16(a, h0, xy[0], 0, 0, 0); xy[1] = __builtin_amdgcn_mfma_f32_16x16x32_bf16(a, h1, xy[1], 0, 0, 0);
;                 xy[0] = __builtin_amdgcn_mfma_f32_16x16x32_bf16(a, l0, xy[0], 0, 0, 0); xy[1] = __builtin_amdgcn_mfma_f32_16x16x32_bf16(a, l1, xy[1], 0, 0, 0);
;             }
;             mm_lds<false>(xs, MAT(0), Pb, mrow, nc0, q);
; #pragma unroll
;             for (int i = 0; i < 2; ++i)
; #pragma unroll
;                 for (int j = 0; j < 4; ++j) { const int r = mt * 16 + 4 * q + j, c2 = nc0 + 16 * i; MAT(1)[r * MS + c2] = xy[i][j] + yv[i][j]; }
;             __syncthreads();
; #pragma unroll
;             for (int i = 0; i < 2; ++i)
; #pragma unroll
;                 for (int j = 0; j < 4; ++j) { const int r = mt * 16 + 4 * q + j, c2 = nc0 + 16 * i; const float sv = xs[i][j] + qv[i][j];
;                     MAT(0)[r * MS + c2] = sv; const bf16_t hb = f2bf(sv); SH[r * BS + c2] = hb; SL[r * BS + c2] = f2bf(sv - bf2f(hb)); }
;             if (cc + 1 < GCH) {
;                 LAS float* Pn = MAT(2 + ((cc + 1) & 1));
;                 *(LAS f32x4*)(Pn + r0 * MS + c0) = n0; *(LAS f32x4*)(Pn + r1 * MS + c1) = n1;
;                 *(LAS u32x4*)((LAS bf16_t*)MAT(6 + ((cc + 1) & 1)) + rr8 * BS + cc8) = rn;
;             }
; #pragma unroll
;             for (int u = 0; u < 8; ++u) {
;                 const int t = tg8 * 8 + u, tok = tok0 + t;
;                 const float y = MAT(1)[t * MS + ci];
;                 const float mean = wave_sum(y) * (1.0f / 64.0f); const float dlt = y - mean;
.LBB0_1062:
	v_cmp_lt_i32_e32 vcc, 0, v42
	s_waitcnt vmcnt(31)
	v_lshlrev_b32_e32 v12, 16, v94
	s_waitcnt vmcnt(30)
	v_lshlrev_b32_e32 v2, 16, v93
	v_cndmask_b32_e64 v3, 0, 1.0, vcc
	v_fma_f32 v2, v3, v2, -v12
	v_cmp_lt_i32_e32 vcc, -1, v42
	v_fmac_f32_e32 v12, v52, v2
	s_waitcnt vmcnt(28)
	v_lshlrev_b32_e32 v13, 16, v91
	s_waitcnt vmcnt(27)
	v_lshlrev_b32_e32 v91, 16, v92
	s_waitcnt vmcnt(26)
	v_lshlrev_b32_e32 v2, 16, v90
	v_cndmask_b32_e64 v3, 0, 1.0, vcc
	v_fma_f32 v2, v3, v2, -v91
	v_fmac_f32_e32 v91, v52, v2
	s_waitcnt vmcnt(23)
	v_lshlrev_b32_e32 v90, 16, v103
	s_waitcnt vmcnt(22)
	v_lshlrev_b32_e32 v2, 16, v104
	v_fma_f32 v2, v3, v2, -v90
	v_fmac_f32_e32 v90, v52, v2
	s_waitcnt vmcnt(19)
	v_lshlrev_b32_e32 v93, 16, v98
	s_waitcnt vmcnt(18)
	v_lshlrev_b32_e32 v2, 16, v99
	v_fma_f32 v2, v3, v2, -v93
	v_fmac_f32_e32 v93, v52, v2
	s_waitcnt vmcnt(16)
	v_lshlrev_b32_e32 v94, 16, v96
	s_waitcnt vmcnt(15)
	v_lshlrev_b32_e32 v8, 16, v109
	s_waitcnt vmcnt(14)
	v_lshlrev_b32_e32 v2, 16, v110
	v_add_u32_e32 v96, 0x4400, v79
	v_fma_f32 v2, v3, v2, -v8
	ds_read2_b32 v[10:11], v96 offset1:68
	v_fmac_f32_e32 v8, v52, v2
	s_waitcnt vmcnt(11)
	v_lshlrev_b32_e32 v6, 16, v107
	s_waitcnt vmcnt(10)
	v_lshlrev_b32_e32 v2, 16, v108
	v_fma_f32 v2, v3, v2, -v6
	v_fmac_f32_e32 v6, v52, v2
	s_waitcnt vmcnt(7)
	v_lshlrev_b32_e32 v4, 16, v111
	s_waitcnt vmcnt(6)
	v_lshlrev_b32_e32 v2, 16, v112
	v_fma_f32 v2, v3, v2, -v4
	v_fmac_f32_e32 v4, v52, v2
	s_waitcnt lgkmcnt(0)
	v_mov_b32_e32 v2, v10
	v_lshlrev_b32_e32 v92, 16, v97
	s_waitcnt vmcnt(2)
	v_lshlrev_b32_e32 v99, 16, v102
	v_mov_b32_dpp v2, v2 quad_perm:[1,0,3,2] row_mask:0xf bank_mask:0xf
	v_add_f32_e32 v2, v10, v2
	v_mov_b32_e32 v5, v2
	v_lshlrev_b32_e32 v89, 16, v89
	v_lshlrev_b32_e32 v9, 16, v106
	v_mov_b32_dpp v5, v5 quad_perm:[2,3,0,1] row_mask:0xf bank_mask:0xf
	v_add_f32_e32 v2, v2, v5
	v_mov_b32_e32 v5, v2
	v_lshlrev_b32_e32 v7, 16, v105
	s_add_i32 s51, s51, 1
	v_mov_b32_dpp v5, v5 row_half_mirror row_mask:0xf bank_mask:0xf
	v_add_f32_e32 v2, v2, v5
	v_mov_b32_e32 v5, v2
	s_add_i32 s10, s10, 8
	s_nop 0
	v_mov_b32_dpp v5, v5 row_mirror row_mask:0xf bank_mask:0xf
	v_add_f32_e32 v2, v2, v5
	s_nop 0
	v_readlane_b32 s7, v2, 16
	v_readlane_b32 s14, v2, 48
	v_readlane_b32 s6, v2, 0
	v_readlane_b32 s11, v2, 32
	v_mov_b32_e32 v2, s7
	v_mov_b32_e32 v5, s14
	v_add_f32_e32 v2, s6, v2
	v_add_f32_e32 v5, s11, v5
	v_add_f32_e32 v2, v2, v5
	v_fmamk_f32 v10, v2, 0xbc800000, v10
	v_mul_f32_e32 v2, v10, v10
	s_nop 1
	v_mov_b32_dpp v2, v2 quad_perm:[1,0,3,2] row_mask:0xf bank_mask:0xf
	v_fmac_f32_e32 v2, v10, v10
	s_nop 1
	v_add_f32_dpp v2, v2, v2 quad_perm:[2,3,0,1] row_mask:0xf bank_mask:0xf
	s_nop 1
	v_add_f32_dpp v2, v2, v2 row_half_mirror row_mask:0xf bank_mask:0xf
	s_nop 1
	v_add_f32_dpp v2, v2, v2 row_mirror row_mask:0xf bank_mask:0xf
	s_nop 0
	v_readlane_b32 s7, v2, 16
	v_readlane_b32 s14, v2, 48
	v_readlane_b32 s6, v2, 0
	v_readlane_b32 s11, v2, 32
	v_mov_b32_e32 v2, s7
	v_mov_b32_e32 v5, s14
	v_add_f32_e32 v2, s6, v2
	v_add_f32_e32 v5, s11, v5
	v_add_f32_e32 v2, v2, v5
	v_fmamk_f32 v2, v2, 0x3c800000, v1
	v_mul_f32_e32 v5, 0x4f800000, v2
	v_cmp_gt_f32_e32 vcc, s48, v2
	s_nop 1
	v_cndmask_b32_e32 v97, v2, v5, vcc
	v_sqrt_f32_e32 v98, v97
	v_lshlrev_b32_e32 v5, 16, v100
	v_lshlrev_b32_e32 v2, 16, v101
	v_fma_f32 v3, v3, v99, -v2
	v_add_u32_e32 v100, -1, v98
	v_fma_f32 v101, -v100, v98, v97
	v_cmp_ge_f32_e64 s[6:7], 0, v101
	v_add_u32_e32 v101, 1, v98
	v_fmac_f32_e32 v2, v52, v3
	v_cndmask_b32_e64 v100, v98, v100, s[6:7]
	v_fma_f32 v98, -v101, v98, v97
	v_cmp_lt_f32_e64 s[6:7], 0, v98
	s_waitcnt vmcnt(0)
	v_lshlrev_b32_e32 v3, 16, v95
	v_cndmask_b32_e64 v98, v100, v101, s[6:7]
	v_mul_f32_e32 v100, 0x37800000, v98
	v_cndmask_b32_e32 v98, v98, v100, vcc
	v_cmp_class_f32_e32 vcc, v97, v44
	s_nop 1
	v_cndmask_b32_e32 v97, v98, v97, vcc
	v_div_scale_f32 v98, s[6:7], v97, v97, 1.0
	v_rcp_f32_e32 v100, v98
	s_nop 0
	v_fma_f32 v95, -v98, v100, 1.0
	v_fmac_f32_e32 v100, v95, v100
	v_div_scale_f32 v95, vcc, 1.0, v97, 1.0
	v_mul_f32_e32 v99, v95, v100
	v_fma_f32 v101, -v98, v99, v95
	v_fmac_f32_e32 v99, v101, v100
	v_fma_f32 v95, -v98, v99, v95
	v_div_fmas_f32 v95, v95, v100, v99
	v_div_fixup_f32 v95, v95, v97, 1.0
	v_mul_f32_e32 v10, v10, v95
	v_mov_b32_e32 v95, v11
	v_fma_f32 v10, v50, v10, v51
	v_fmac_f32_e32 v10, v88, v12
	v_mov_b32_dpp v95, v95 quad_perm:[1,0,3,2] row_mask:0xf bank_mask:0xf
	v_add_f32_e32 v95, v11, v95
	v_mov_b32_e32 v97, v95
	v_mul_f32_e32 v10, v10, v13
	v_cvt_pk_bf16_f32 v10, v10, s0
	v_mov_b32_dpp v97, v97 quad_perm:[2,3,0,1] row_mask:0xf bank_mask:0xf
	v_add_f32_e32 v95, v95, v97
	s_nop 1
	v_add_f32_dpp v95, v95, v95 row_half_mirror row_mask:0xf bank_mask:0xf
	s_nop 1
	v_add_f32_dpp v95, v95, v95 row_mirror row_mask:0xf bank_mask:0xf
	s_nop 0
	v_readlane_b32 s7, v95, 16
	v_readlane_b32 s14, v95, 48
	v_readlane_b32 s6, v95, 0
	v_readlane_b32 s11, v95, 32
	v_mov_b32_e32 v95, s7
	v_mov_b32_e32 v97, s14
	v_add_f32_e32 v95, s6, v95
	v_add_f32_e32 v97, s11, v97
	v_add_f32_e32 v95, v95, v97
	v_fmac_f32_e32 v11, 0xbc800000, v95
	v_mul_f32_e32 v95, v11, v11
	s_nop 1
	v_mov_b32_dpp v95, v95 quad_perm:[1,0,3,2] row_mask:0xf bank_mask:0xf
	v_fmac_f32_e32 v95, v11, v11
	s_nop 1
	v_add_f32_dpp v95, v95, v95 quad_perm:[2,3,0,1] row_mask:0xf bank_mask:0xf
	s_nop 1
	v_add_f32_dpp v95, v95, v95 row_half_mirror row_mask:0xf bank_mask:0xf
	s_nop 1
	v_add_f32_dpp v95, v95, v95 row_mirror row_mask:0xf bank_mask:0xf
	s_nop 0
	v_readlane_b32 s7, v95, 16
	v_readlane_b32 s14, v95, 48
	v_readlane_b32 s6, v95, 0
	v_readlane_b32 s11, v95, 32
	v_mov_b32_e32 v95, s7
	v_mov_b32_e32 v97, s14
	v_add_f32_e32 v95, s6, v95
	v_add_f32_e32 v97, s11, v97
	v_add_f32_e32 v95, v95, v97
	v_fmamk_f32 v95, v95, 0x3c800000, v1
	v_mul_f32_e32 v97, 0x4f800000, v95
	v_cmp_gt_f32_e32 vcc, s48, v95
	s_nop 1
	v_cndmask_b32_e32 v95, v95, v97, vcc
	v_sqrt_f32_e32 v97, v95
	s_nop 0
	v_add_u32_e32 v12, -1, v97
	v_fma_f32 v13, -v12, v97, v95
	v_cmp_ge_f32_e64 s[6:7], 0, v13
	v_add_u32_e32 v13, 1, v97
	v_fma_f32 v88, -v13, v97, v95
	v_cndmask_b32_e64 v12, v97, v12, s[6:7]
	v_cmp_lt_f32_e64 s[6:7], 0, v88
	s_nop 1
	v_cndmask_b32_e64 v12, v12, v13, s[6:7]
	v_mul_f32_e32 v13, 0x37800000, v12
	v_cndmask_b32_e32 v12, v12, v13, vcc
	v_cmp_class_f32_e32 vcc, v95, v44
	s_nop 1
	v_cndmask_b32_e32 v88, v12, v95, vcc
	v_div_scale_f32 v95, s[6:7], v88, v88, 1.0
	v_rcp_f32_e32 v97, v95
	v_lshlrev_b64 v[12:13], 11, v[42:43]
	v_lshl_add_u64 v[12:13], v[22:23], 0, v[12:13]
	global_store_short v[12:13], v10, off
	v_fma_f32 v10, -v95, v97, 1.0
	v_fmac_f32_e32 v97, v10, v97
	v_div_scale_f32 v10, vcc, 1.0, v88, 1.0
	v_mul_f32_e32 v42, v10, v97
	v_fma_f32 v12, -v95, v42, v10
	v_fmac_f32_e32 v42, v12, v97
	ds_read2_b32 v[12:13], v96 offset0:136 offset1:204
	v_fma_f32 v10, -v95, v42, v10
	v_div_fmas_f32 v10, v10, v97, v42
	v_div_fixup_f32 v10, v10, v88, 1.0
	v_mul_f32_e32 v10, v11, v10
	s_waitcnt lgkmcnt(0)
; __device__ __forceinline__ bf16_t f2bf(float f) { return (bf16_t)(pk2(f, 0.f) & 0xffffu); }
; __device__ __forceinline__ void rwkv_phase_c(const Ctx& C) {
;     ...
;             for (int u = 0; u < 8; ++u) {
;                 const int t = tg8 * 8 + u, tok = tok0 + t;
;                 const float y = MAT(1)[t * MS + ci];
;                 const float mean = wave_sum(y) * (1.0f / 64.0f); const float dlt = y - mean;
;                 const float var = wave_sum(dlt * dlt) * (1.0f / 64.0f);
;                 const float yn = dlt * (1.0f / sqrtf(var + 64e-5f)) * gg + gb;
;                 ycat[(size_t)tok * D_ + h * 64 + ci] = f2bf((yn + bo[u] * vv[u]) * gt[u]);
	v_mov_b32_e32 v11, v12
	v_fma_f32 v10, v50, v10, v51
	v_fmac_f32_e32 v10, v87, v91
	v_mov_b32_dpp v11, v11 quad_perm:[1,0,3,2] row_mask:0xf bank_mask:0xf
	v_add_f32_e32 v11, v12, v11
	v_mov_b32_e32 v42, v11
	v_mul_f32_e32 v10, v10, v89
	v_cvt_pk_bf16_f32 v43, v10, s0
	v_mov_b32_dpp v42, v42 quad_perm:[2,3,0,1] row_mask:0xf bank_mask:0xf
	v_add_f32_e32 v11, v11, v42
	s_nop 1
	v_add_f32_dpp v11, v11, v11 row_half_mirror row_mask:0xf bank_mask:0xf
	s_nop 1
	v_add_f32_dpp v11, v11, v11 row_mirror row_mask:0xf bank_mask:0xf
	s_nop 0
	v_readlane_b32 s7, v11, 16
	v_readlane_b32 s14, v11, 48
	v_readlane_b32 s6, v11, 0
	v_readlane_b32 s11, v11, 32
	v_mov_b32_e32 v11, s7
	v_mov_b32_e32 v42, s14
	v_add_f32_e32 v11, s6, v11
	v_add_f32_e32 v42, s11, v42
	v_add_f32_e32 v11, v11, v42
	v_fmamk_f32 v12, v11, 0xbc800000, v12
	v_mul_f32_e32 v11, v12, v12
	s_nop 1
	v_mov_b32_dpp v11, v11 quad_perm:[1,0,3,2] row_mask:0xf bank_mask:0xf
	v_fmac_f32_e32 v11, v12, v12
	s_nop 1
	v_add_f32_dpp v11, v11, v11 quad_perm:[2,3,0,1] row_mask:0xf bank_mask:0xf
	s_nop 1
	v_add_f32_dpp v11, v11, v11 row_half_mirror row_mask:0xf bank_mask:0xf
	s_nop 1
	v_add_f32_dpp v11, v11, v11 row_mirror row_mask:0xf bank_mask:0xf
	s_nop 0
	v_readlane_b32 s7, v11, 16
	v_readlane_b32 s14, v11, 48
	v_readlane_b32 s6, v11, 0
	v_readlane_b32 s11, v11, 32
	v_mov_b32_e32 v11, s7
	v_mov_b32_e32 v42, s14
	v_add_f32_e32 v11, s6, v11
	v_add_f32_e32 v42, s11, v42
	v_add_f32_e32 v11, v11, v42
	v_fmamk_f32 v11, v11, 0x3c800000, v1
	v_mul_f32_e32 v42, 0x4f800000, v11
	v_cmp_gt_f32_e32 vcc, s48, v11
	s_nop 1
	v_cndmask_b32_e32 v11, v11, v42, vcc
	v_sqrt_f32_e32 v42, v11
	s_nop 0
	v_add_u32_e32 v10, -1, v42
	v_fma_f32 v87, -v10, v42, v11
	v_cmp_ge_f32_e64 s[6:7], 0, v87
	v_add_u32_e32 v87, 1, v42
	s_nop 0
	v_cndmask_b32_e64 v10, v42, v10, s[6:7]
	v_fma_f32 v42, -v87, v42, v11
	v_cmp_lt_f32_e64 s[6:7], 0, v42
	s_nop 1
	v_cndmask_b32_e64 v10, v10, v87, s[6:7]
	v_mul_f32_e32 v42, 0x37800000, v10
	v_cndmask_b32_e32 v10, v10, v42, vcc
	v_cmp_class_f32_e32 vcc, v11, v44
	s_nop 1
	v_cndmask_b32_e32 v42, v10, v11, vcc
	v_div_scale_f32 v87, s[6:7], v42, v42, 1.0
	v_rcp_f32_e32 v88, v87
	v_lshlrev_b64 v[10:11], 11, v[40:41]
	v_lshl_add_u64 v[10:11], v[22:23], 0, v[10:11]
	global_store_short v[10:11], v43, off
	v_fma_f32 v10, -v87, v88, 1.0
	v_fmac_f32_e32 v88, v10, v88
	v_div_scale_f32 v10, vcc, 1.0, v42, 1.0
	v_mul_f32_e32 v11, v10, v88
	v_fma_f32 v40, -v87, v11, v10
	v_fmac_f32_e32 v11, v40, v88
	v_fma_f32 v10, -v87, v11, v10
	v_div_fmas_f32 v10, v10, v88, v11
	v_mov_b32_e32 v11, v13
	v_div_fixup_f32 v10, v10, v42, 1.0
	v_mul_f32_e32 v10, v12, v10
	v_mov_b32_dpp v11, v11 quad_perm:[1,0,3,2] row_mask:0xf bank_mask:0xf
	v_add_f32_e32 v11, v13, v11
	v_mov_b32_e32 v12, v11
	v_fma_f32 v10, v50, v10, v51
	v_fmac_f32_e32 v10, v86, v90
	v_mov_b32_dpp v12, v12 quad_perm:[2,3,0,1] row_mask:0xf bank_mask:0xf
	v_add_f32_e32 v11, v11, v12
	v_mov_b32_e32 v12, v11
	v_mul_f32_e32 v10, v10, v92
	v_cvt_pk_bf16_f32 v40, v10, s0
	v_mov_b32_dpp v12, v12 row_half_mirror row_mask:0xf bank_mask:0xf
	v_add_f32_e32 v11, v11, v12
	s_nop 1
	v_add_f32_dpp v11, v11, v11 row_mirror row_mask:0xf bank_mask:0xf
	s_nop 0
	v_readlane_b32 s7, v11, 16
	v_readlane_b32 s14, v11, 48
	v_readlane_b32 s6, v11, 0
	v_readlane_b32 s11, v11, 32
	v_mov_b32_e32 v11, s7
	v_mov_b32_e32 v12, s14
	v_add_f32_e32 v11, s6, v11
	v_add_f32_e32 v12, s11, v12
	v_add_f32_e32 v11, v11, v12
	v_fmac_f32_e32 v13, 0xbc800000, v11
	v_mul_f32_e32 v11, v13, v13
	s_nop 1
	v_mov_b32_dpp v11, v11 quad_perm:[1,0,3,2] row_mask:0xf bank_mask:0xf
	v_fmac_f32_e32 v11, v13, v13
	s_nop 1
	v_add_f32_dpp v11, v11, v11 quad_perm:[2,3,0,1] row_mask:0xf bank_mask:0xf
	s_nop 1
	v_add_f32_dpp v11, v11, v11 row_half_mirror row_mask:0xf bank_mask:0xf
	s_nop 1
	v_add_f32_dpp v11, v11, v11 row_mirror row_mask:0xf bank_mask:0xf
	s_nop 0
	v_readlane_b32 s7, v11, 16
	v_readlane_b32 s14, v11, 48
	v_readlane_b32 s6, v11, 0
	v_readlane_b32 s11, v11, 32
	v_mov_b32_e32 v11, s7
	v_mov_b32_e32 v12, s14
	v_add_f32_e32 v11, s6, v11
	v_add_f32_e32 v12, s11, v12
	v_add_f32_e32 v11, v11, v12
	v_fmamk_f32 v11, v11, 0x3c800000, v1
	v_mul_f32_e32 v12, 0x4f800000, v11
	v_cmp_gt_f32_e32 vcc, s48, v11
	s_nop 1
	v_cndmask_b32_e32 v11, v11, v12, vcc
	v_sqrt_f32_e32 v12, v11
	s_nop 0
	v_add_u32_e32 v10, -1, v12
	v_fma_f32 v41, -v10, v12, v11
	v_cmp_ge_f32_e64 s[6:7], 0, v41
	v_add_u32_e32 v41, 1, v12
	s_nop 0
	v_cndmask_b32_e64 v10, v12, v10, s[6:7]
	v_fma_f32 v12, -v41, v12, v11
	v_cmp_lt_f32_e64 s[6:7], 0, v12
	s_nop 1
	v_cndmask_b32_e64 v10, v10, v41, s[6:7]
	v_mul_f32_e32 v12, 0x37800000, v10
	v_cndmask_b32_e32 v10, v10, v12, vcc
	v_cmp_class_f32_e32 vcc, v11, v44
	s_nop 1
	v_cndmask_b32_e32 v12, v10, v11, vcc
	v_div_scale_f32 v41, s[6:7], v12, v12, 1.0
	v_rcp_f32_e32 v42, v41
	v_lshlrev_b64 v[10:11], 11, v[38:39]
	v_lshl_add_u64 v[10:11], v[22:23], 0, v[10:11]
	global_store_short v[10:11], v40, off
	v_fma_f32 v10, -v41, v42, 1.0
	v_fmac_f32_e32 v42, v10, v42
	v_div_scale_f32 v10, vcc, 1.0, v12, 1.0
	v_mul_f32_e32 v38, v10, v42
	v_fma_f32 v11, -v41, v38, v10
	v_fmac_f32_e32 v38, v11, v42
	v_fma_f32 v39, -v41, v38, v10
	v_add_u32_e32 v10, 0x4800, v79
	ds_read2_b32 v[10:11], v10 offset0:16 offset1:84
	v_div_fmas_f32 v38, v39, v42, v38
	v_div_fixup_f32 v12, v38, v12, 1.0
	v_mul_f32_e32 v12, v13, v12
	v_fma_f32 v12, v50, v12, v51
	s_waitcnt lgkmcnt(0)
; __device__ __forceinline__ bf16_t f2bf(float f) { return (bf16_t)(pk2(f, 0.f) & 0xffffu); }
; __device__ __forceinline__ void rwkv_phase_c(const Ctx& C) {
;     ...
;             for (int u = 0; u < 8; ++u) {
;                 const int t = tg8 * 8 + u, tok = tok0 + t;
;                 const float y = MAT(1)[t * MS + ci];
;                 const float mean = wave_sum(y) * (1.0f / 64.0f); const float dlt = y - mean;
;                 const float var = wave_sum(dlt * dlt) * (1.0f / 64.0f);
;                 const float yn = dlt * (1.0f / sqrtf(var + 64e-5f)) * gg + gb;
;                 ycat[(size_t)tok * D_ + h * 64 + ci] = f2bf((yn + bo[u] * vv[u]) * gt[u]);
	v_mov_b32_e32 v13, v10
	v_fmac_f32_e32 v12, v85, v93
	v_mul_f32_e32 v12, v12, v94
	v_mov_b32_dpp v13, v13 quad_perm:[1,0,3,2] row_mask:0xf bank_mask:0xf
	v_add_f32_e32 v13, v10, v13
	v_mov_b32_e32 v38, v13
	v_cvt_pk_bf16_f32 v39, v12, s0
	s_nop 0
	v_mov_b32_dpp v38, v38 quad_perm:[2,3,0,1] row_mask:0xf bank_mask:0xf
	v_add_f32_e32 v13, v13, v38
	s_nop 1
	v_add_f32_dpp v13, v13, v13 row_half_mirror row_mask:0xf bank_mask:0xf
	s_nop 1
	v_add_f32_dpp v13, v13, v13 row_mirror row_mask:0xf bank_mask:0xf
	s_nop 0
	v_readlane_b32 s7, v13, 16
	v_readlane_b32 s14, v13, 48
	v_readlane_b32 s6, v13, 0
	v_readlane_b32 s11, v13, 32
	v_mov_b32_e32 v13, s7
	v_mov_b32_e32 v38, s14
	v_add_f32_e32 v13, s6, v13
	v_add_f32_e32 v38, s11, v38
	v_add_f32_e32 v13, v13, v38
	v_fmamk_f32 v10, v13, 0xbc800000, v10
	v_mul_f32_e32 v13, v10, v10
	s_nop 1
	v_mov_b32_dpp v13, v13 quad_perm:[1,0,3,2] row_mask:0xf bank_mask:0xf
	v_fmac_f32_e32 v13, v10, v10
	s_nop 1
	v_add_f32_dpp v13, v13, v13 quad_perm:[2,3,0,1] row_mask:0xf bank_mask:0xf
	s_nop 1
	v_add_f32_dpp v13, v13, v13 row_half_mirror row_mask:0xf bank_mask:0xf
	s_nop 1
	v_add_f32_dpp v13, v13, v13 row_mirror row_mask:0xf bank_mask:0xf
	s_nop 0
	v_readlane_b32 s7, v13, 16
	v_readlane_b32 s14, v13, 48
	v_readlane_b32 s6, v13, 0
	v_readlane_b32 s11, v13, 32
	v_mov_b32_e32 v13, s7
	v_mov_b32_e32 v38, s14
	v_add_f32_e32 v13, s6, v13
	v_add_f32_e32 v38, s11, v38
	v_add_f32_e32 v13, v13, v38
	v_fmamk_f32 v13, v13, 0x3c800000, v1
	v_mul_f32_e32 v38, 0x4f800000, v13
	v_cmp_gt_f32_e32 vcc, s48, v13
	s_nop 1
	v_cndmask_b32_e32 v13, v13, v38, vcc
	v_sqrt_f32_e32 v38, v13
	s_nop 0
	v_add_u32_e32 v12, -1, v38
	v_fma_f32 v40, -v12, v38, v13
	v_cmp_ge_f32_e64 s[6:7], 0, v40
	v_add_u32_e32 v40, 1, v38
	s_nop 0
	v_cndmask_b32_e64 v12, v38, v12, s[6:7]
	v_fma_f32 v38, -v40, v38, v13
	v_cmp_lt_f32_e64 s[6:7], 0, v38
	s_nop 1
	v_cndmask_b32_e64 v12, v12, v40, s[6:7]
	v_mul_f32_e32 v38, 0x37800000, v12
	v_cndmask_b32_e32 v12, v12, v38, vcc
	v_cmp_class_f32_e32 vcc, v13, v44
	s_nop 1
	v_cndmask_b32_e32 v38, v12, v13, vcc
	v_div_scale_f32 v40, s[6:7], v38, v38, 1.0
	v_rcp_f32_e32 v41, v40
	v_lshlrev_b64 v[12:13], 11, v[36:37]
	v_lshl_add_u64 v[12:13], v[22:23], 0, v[12:13]
	global_store_short v[12:13], v39, off
	v_fma_f32 v12, -v40, v41, 1.0
	v_fmac_f32_e32 v41, v12, v41
	v_div_scale_f32 v12, vcc, 1.0, v38, 1.0
	v_mul_f32_e32 v13, v12, v41
	v_fma_f32 v36, -v40, v13, v12
	v_fmac_f32_e32 v13, v36, v41
	v_fma_f32 v12, -v40, v13, v12
	v_div_fmas_f32 v12, v12, v41, v13
	v_div_fixup_f32 v12, v12, v38, 1.0
	v_mul_f32_e32 v10, v10, v12
	v_mov_b32_e32 v12, v11
	v_fma_f32 v10, v50, v10, v51
	v_fmac_f32_e32 v10, v84, v8
	v_mov_b32_dpp v12, v12 quad_perm:[1,0,3,2] row_mask:0xf bank_mask:0xf
	v_add_f32_e32 v12, v11, v12
	v_mov_b32_e32 v13, v12
	v_mul_f32_e32 v8, v10, v9
	v_cvt_pk_bf16_f32 v10, v8, s0
	v_mov_b32_dpp v13, v13 quad_perm:[2,3,0,1] row_mask:0xf bank_mask:0xf
	v_add_f32_e32 v12, v12, v13
	s_nop 1
	v_add_f32_dpp v12, v12, v12 row_half_mirror row_mask:0xf bank_mask:0xf
	s_nop 1
	v_add_f32_dpp v12, v12, v12 row_mirror row_mask:0xf bank_mask:0xf
	s_nop 0
	v_readlane_b32 s7, v12, 16
	v_readlane_b32 s14, v12, 48
	v_readlane_b32 s6, v12, 0
	v_readlane_b32 s11, v12, 32
	v_mov_b32_e32 v12, s7
	v_mov_b32_e32 v13, s14
	v_add_f32_e32 v12, s6, v12
	v_add_f32_e32 v13, s11, v13
	v_add_f32_e32 v12, v12, v13
	v_fmac_f32_e32 v11, 0xbc800000, v12
	v_mul_f32_e32 v12, v11, v11
	s_nop 1
	v_mov_b32_dpp v12, v12 quad_perm:[1,0,3,2] row_mask:0xf bank_mask:0xf
	v_fmac_f32_e32 v12, v11, v11
	s_nop 1
	v_add_f32_dpp v12, v12, v12 quad_perm:[2,3,0,1] row_mask:0xf bank_mask:0xf
	s_nop 1
	v_add_f32_dpp v12, v12, v12 row_half_mirror row_mask:0xf bank_mask:0xf
	s_nop 1
	v_add_f32_dpp v12, v12, v12 row_mirror row_mask:0xf bank_mask:0xf
	s_nop 0
	v_readlane_b32 s7, v12, 16
	v_readlane_b32 s14, v12, 48
	v_readlane_b32 s6, v12, 0
	v_readlane_b32 s11, v12, 32
	v_mov_b32_e32 v12, s7
	v_mov_b32_e32 v13, s14
	v_add_f32_e32 v12, s6, v12
	v_add_f32_e32 v13, s11, v13
	v_add_f32_e32 v12, v12, v13
	v_fmamk_f32 v12, v12, 0x3c800000, v1
	v_mul_f32_e32 v13, 0x4f800000, v12
	v_cmp_gt_f32_e32 vcc, s48, v12
	s_nop 1
	v_cndmask_b32_e32 v12, v12, v13, vcc
	v_sqrt_f32_e32 v13, v12
	s_nop 0
	v_add_u32_e32 v8, -1, v13
	v_fma_f32 v9, -v8, v13, v12
	v_cmp_ge_f32_e64 s[6:7], 0, v9
	v_add_u32_e32 v9, 1, v13
	s_nop 0
	v_cndmask_b32_e64 v8, v13, v8, s[6:7]
	v_fma_f32 v13, -v9, v13, v12
	v_cmp_lt_f32_e64 s[6:7], 0, v13
	s_nop 1
	v_cndmask_b32_e64 v8, v8, v9, s[6:7]
	v_mul_f32_e32 v9, 0x37800000, v8
	v_cndmask_b32_e32 v8, v8, v9, vcc
	v_cmp_class_f32_e32 vcc, v12, v44
	s_nop 1
	v_cndmask_b32_e32 v12, v8, v12, vcc
	v_div_scale_f32 v13, s[6:7], v12, v12, 1.0
	v_rcp_f32_e32 v36, v13
	v_lshlrev_b64 v[8:9], 11, v[34:35]
	v_lshl_add_u64 v[8:9], v[22:23], 0, v[8:9]
	global_store_short v[8:9], v10, off
	v_fma_f32 v8, -v13, v36, 1.0
	v_fmac_f32_e32 v36, v8, v36
	v_div_scale_f32 v8, vcc, 1.0, v12, 1.0
	v_mul_f32_e32 v9, v8, v36
	v_fma_f32 v10, -v13, v9, v8
	v_fmac_f32_e32 v9, v10, v36
	v_fma_f32 v8, -v13, v9, v8
	v_div_fmas_f32 v8, v8, v36, v9
	ds_read_b32 v9, v79 offset:19040
	ds_read_b32 v10, v80 offset:17408
	v_div_fixup_f32 v8, v8, v12, 1.0
	v_mul_f32_e32 v8, v11, v8
	v_fma_f32 v8, v50, v8, v51
	s_waitcnt lgkmcnt(1)
; __device__ __forceinline__ bf16_t f2bf(float f) { return (bf16_t)(pk2(f, 0.f) & 0xffffu); }
; __device__ __forceinline__ void rwkv_phase_c(const Ctx& C) {
;     ...
;             for (int u = 0; u < 8; ++u) {
;                 const int t = tg8 * 8 + u, tok = tok0 + t;
;                 const float y = MAT(1)[t * MS + ci];
;                 const float mean = wave_sum(y) * (1.0f / 64.0f); const float dlt = y - mean;
;                 const float var = wave_sum(dlt * dlt) * (1.0f / 64.0f);
;                 const float yn = dlt * (1.0f / sqrtf(var + 64e-5f)) * gg + gb;
;                 ycat[(size_t)tok * D_ + h * 64 + ci] = f2bf((yn + bo[u] * vv[u]) * gt[u]);
;             }
;             __syncthreads();
	v_mov_b32_e32 v11, v9
	v_fmac_f32_e32 v8, v82, v6
	v_mul_f32_e32 v6, v8, v7
	v_mov_b32_dpp v11, v11 quad_perm:[1,0,3,2] row_mask:0xf bank_mask:0xf
	v_add_f32_e32 v11, v9, v11
	v_mov_b32_e32 v12, v11
	v_cvt_pk_bf16_f32 v8, v6, s0
	s_nop 0
	v_mov_b32_dpp v12, v12 quad_perm:[2,3,0,1] row_mask:0xf bank_mask:0xf
	v_add_f32_e32 v11, v11, v12
	s_nop 1
	v_add_f32_dpp v11, v11, v11 row_half_mirror row_mask:0xf bank_mask:0xf
	s_nop 1
	v_add_f32_dpp v11, v11, v11 row_mirror row_mask:0xf bank_mask:0xf
	s_nop 0
	v_readlane_b32 s7, v11, 16
	v_readlane_b32 s14, v11, 48
	v_readlane_b32 s6, v11, 0
	v_readlane_b32 s11, v11, 32
	v_mov_b32_e32 v11, s7
	v_mov_b32_e32 v12, s14
	v_add_f32_e32 v11, s6, v11
	v_add_f32_e32 v12, s11, v12
	v_add_f32_e32 v11, v11, v12
	v_fmac_f32_e32 v9, 0xbc800000, v11
	v_mul_f32_e32 v11, v9, v9
	s_nop 1
	v_mov_b32_dpp v11, v11 quad_perm:[1,0,3,2] row_mask:0xf bank_mask:0xf
	v_fmac_f32_e32 v11, v9, v9
	s_nop 1
	v_add_f32_dpp v11, v11, v11 quad_perm:[2,3,0,1] row_mask:0xf bank_mask:0xf
	s_nop 1
	v_add_f32_dpp v11, v11, v11 row_half_mirror row_mask:0xf bank_mask:0xf
	s_nop 1
	v_add_f32_dpp v11, v11, v11 row_mirror row_mask:0xf bank_mask:0xf
	s_nop 0
	v_readlane_b32 s7, v11, 16
	v_readlane_b32 s14, v11, 48
	v_readlane_b32 s6, v11, 0
	v_readlane_b32 s11, v11, 32
	v_mov_b32_e32 v11, s7
	v_mov_b32_e32 v12, s14
	v_add_f32_e32 v11, s6, v11
	v_add_f32_e32 v12, s11, v12
	v_add_f32_e32 v11, v11, v12
	v_fmamk_f32 v11, v11, 0x3c800000, v1
	v_mul_f32_e32 v12, 0x4f800000, v11
	v_cmp_gt_f32_e32 vcc, s48, v11
	s_nop 1
	v_cndmask_b32_e32 v11, v11, v12, vcc
	v_sqrt_f32_e32 v12, v11
	s_nop 0
	v_add_u32_e32 v6, -1, v12
	v_fma_f32 v7, -v6, v12, v11
	v_cmp_ge_f32_e64 s[6:7], 0, v7
	v_add_u32_e32 v7, 1, v12
	s_nop 0
	v_cndmask_b32_e64 v6, v12, v6, s[6:7]
	v_fma_f32 v12, -v7, v12, v11
	v_cmp_lt_f32_e64 s[6:7], 0, v12
	s_nop 1
	v_cndmask_b32_e64 v6, v6, v7, s[6:7]
	v_mul_f32_e32 v7, 0x37800000, v6
	v_cndmask_b32_e32 v6, v6, v7, vcc
	v_cmp_class_f32_e32 vcc, v11, v44
	s_nop 1
	v_cndmask_b32_e32 v11, v6, v11, vcc
	v_div_scale_f32 v12, s[6:7], v11, v11, 1.0
	v_rcp_f32_e32 v13, v12
	v_lshlrev_b64 v[6:7], 11, v[32:33]
	v_lshl_add_u64 v[6:7], v[22:23], 0, v[6:7]
	global_store_short v[6:7], v8, off
	v_fma_f32 v6, -v12, v13, 1.0
	v_fmac_f32_e32 v13, v6, v13
	v_div_scale_f32 v6, vcc, 1.0, v11, 1.0
	v_mul_f32_e32 v7, v6, v13
	v_fma_f32 v8, -v12, v7, v6
	v_fmac_f32_e32 v7, v8, v13
	v_fma_f32 v6, -v12, v7, v6
	v_div_fmas_f32 v6, v6, v13, v7
	v_div_fixup_f32 v6, v6, v11, 1.0
	v_mul_f32_e32 v6, v9, v6
	v_fma_f32 v6, v50, v6, v51
	v_fmac_f32_e32 v6, v83, v4
	s_waitcnt lgkmcnt(0)
	s_nop 1
	v_add_f32_dpp v4, v10, v10 quad_perm:[1,0,3,2] row_mask:0xf bank_mask:0xf
	s_nop 1
	v_add_f32_dpp v4, v4, v4 quad_perm:[2,3,0,1] row_mask:0xf bank_mask:0xf
	s_nop 1
	v_add_f32_dpp v4, v4, v4 row_half_mirror row_mask:0xf bank_mask:0xf
	s_nop 1
	v_add_f32_dpp v4, v4, v4 row_mirror row_mask:0xf bank_mask:0xf
	s_nop 0
	v_readlane_b32 s7, v4, 16
	v_readlane_b32 s14, v4, 48
	v_readlane_b32 s6, v4, 0
	v_readlane_b32 s11, v4, 32
	v_mov_b32_e32 v4, s7
	v_mov_b32_e32 v7, s14
	v_add_f32_e32 v4, s6, v4
	v_add_f32_e32 v7, s11, v7
	v_add_f32_e32 v4, v4, v7
	v_fmac_f32_e32 v10, 0xbc800000, v4
	v_mul_f32_e32 v4, v10, v10
	s_nop 1
	v_mov_b32_dpp v4, v4 quad_perm:[1,0,3,2] row_mask:0xf bank_mask:0xf
	v_fmac_f32_e32 v4, v10, v10
	s_nop 1
	v_add_f32_dpp v4, v4, v4 quad_perm:[2,3,0,1] row_mask:0xf bank_mask:0xf
	s_nop 1
	v_add_f32_dpp v4, v4, v4 row_half_mirror row_mask:0xf bank_mask:0xf
	s_nop 1
	v_add_f32_dpp v4, v4, v4 row_mirror row_mask:0xf bank_mask:0xf
	s_nop 0
	v_readlane_b32 s7, v4, 16
	v_readlane_b32 s14, v4, 48
	v_readlane_b32 s6, v4, 0
	v_readlane_b32 s11, v4, 32
	v_mov_b32_e32 v4, s7
	v_mov_b32_e32 v7, s14
	v_add_f32_e32 v4, s6, v4
	v_add_f32_e32 v7, s11, v7
	v_add_f32_e32 v4, v4, v7
	v_fmamk_f32 v4, v4, 0x3c800000, v1
	v_mul_f32_e32 v7, 0x4f800000, v4
	v_cmp_gt_f32_e32 vcc, s48, v4
	s_nop 1
	v_cndmask_b32_e32 v7, v4, v7, vcc
	v_sqrt_f32_e32 v8, v7
	v_mul_f32_e32 v4, v6, v5
	v_cvt_pk_bf16_f32 v6, v4, s0
	v_lshlrev_b64 v[4:5], 11, v[30:31]
	v_add_u32_e32 v9, -1, v8
	v_fma_f32 v11, -v9, v8, v7
	v_cmp_ge_f32_e64 s[6:7], 0, v11
	v_add_u32_e32 v11, 1, v8
	v_lshl_add_u64 v[4:5], v[22:23], 0, v[4:5]
	v_cndmask_b32_e64 v9, v8, v9, s[6:7]
	v_fma_f32 v8, -v11, v8, v7
	v_cmp_lt_f32_e64 s[6:7], 0, v8
	global_store_short v[4:5], v6, off
	v_add_u32_e32 v4, s54, v75
	v_cndmask_b32_e64 v8, v9, v11, s[6:7]
	v_mul_f32_e32 v9, 0x37800000, v8
	v_cndmask_b32_e32 v8, v8, v9, vcc
	v_cmp_class_f32_e32 vcc, v7, v44
	s_add_i32 s54, s54, 64
	s_cmpk_eq_i32 s54, 0x200
	v_cndmask_b32_e32 v7, v8, v7, vcc
	v_div_scale_f32 v8, s[6:7], v7, v7, 1.0
	v_rcp_f32_e32 v9, v8
	s_nop 0
	v_fma_f32 v5, -v8, v9, 1.0
	v_fmac_f32_e32 v9, v5, v9
	v_div_scale_f32 v5, vcc, 1.0, v7, 1.0
	v_mul_f32_e32 v6, v5, v9
	v_fma_f32 v11, -v8, v6, v5
	v_fmac_f32_e32 v6, v11, v9
	v_fma_f32 v5, -v8, v6, v5
	v_div_fmas_f32 v5, v5, v9, v6
	v_div_fixup_f32 v5, v5, v7, 1.0
	v_mul_f32_e32 v5, v10, v5
	v_fma_f32 v5, v50, v5, v51
	v_fmac_f32_e32 v5, v81, v2
	v_mul_f32_e32 v2, v5, v3
	v_ashrrev_i32_e32 v5, 31, v4
	v_cvt_pk_bf16_f32 v6, v2, s0
	v_lshlrev_b64 v[2:3], 11, v[4:5]
	v_lshl_add_u64 v[2:3], v[22:23], 0, v[2:3]
	global_store_short v[2:3], v6, off
	s_barrier
	s_cbranch_scc1 .LBB0_1060
